# pool_d: one item per thread = two consecutive rows (34 loads in one round trip instead of two passes of 30)
# baseline (speedup 1.0000x reference)
; __device__ __forceinline__ float bflo(unsigned w) { return __uint_as_float(w << 16); }
; __device__ __forceinline__ float bfhi(unsigned w) { return __uint_as_float(w & 0xffff0000u); }
; template <int W>
; __device__ __forceinline__ void pool_item(const Params& p, const bf16_t* PROJ, bf16_t* D, int r, int c0) {
;     float sum[8], uu[8];
;     const u32x4 v0 = *(const u32x4*)(PROJ + (size_t)r * NQ + c0);
;     uu[0] = bflo(v0.x); uu[1] = bfhi(v0.x); uu[2] = bflo(v0.y); uu[3] = bfhi(v0.y); uu[4] = bflo(v0.z); uu[5] = bfhi(v0.z); uu[6] = bflo(v0.w); uu[7] = bfhi(v0.w);
; #pragma unroll
;     for (int j = 0; j < 8; ++j) sum[j] = uu[j];
;     float cnt;
;     if (r < MP) {
;         const int t = r & 2047; cnt = (float)((t + 1 < W) ? (t + 1) : W);
;         u32x4 v[W - 1];
; #pragma unroll
;         for (int i = 1; i < W; ++i) v[i - 1] = *(const u32x4*)(PROJ + (size_t)(r - (i <= t ? i : 0)) * NQ + c0);
; #pragma unroll
;         for (int i = 1; i < W; ++i) acc8(sum, v[i - 1], (i <= t) ? 1.f : 0.f);
; __device__ __forceinline__ void phase_pool_d(const Params& p, int wave_s) {
;     const bf16_t* PROJ = (const bf16_t*)(p.ws + WS_PROJ); bf16_t* D = (bf16_t*)(p.ws + WS_D);
;     const int total = MR * 32;
;     const int tid = opaque_tid(wave_s);
;     for (int idx = blockIdx.x * 512 + tid; idx < total; idx += gridDim.x * 512) {
;         const int r = idx >> 5, ch = idx & 31;
;         pool_item<2>(p, PROJ, D, r, ch * 8);
;         pool_item<4>(p, PROJ, D, r, 256 + ch * 8);
;         pool_item<8>(p, PROJ, D, r, 512 + ch * 8);
;         pool_item<16>(p, PROJ, D, r, 768 + ch * 8);
.LBB0_641:
	s_cmp_lt_i32 s18, 3
	s_cselect_b64 s[4:5], -1, 0
	s_and_b64 s[26:27], s[4:5], s[0:1]
	s_andn2_b64 vcc, exec, s[26:27]
	s_cbranch_vccnz .LBB0_787
	s_mov_b32 s32, 0
	s_add_i32 s79, s2, 0x600
	s_mov_b64 exec, -1
	s_add_u32 s28, s22, 0xa6aa000
	s_addc_u32 s29, s23, 0
	s_add_u32 s84, s22, 0x64aa000
	s_addc_u32 s85, s23, 0
	v_mbcnt_lo_u32_b32 v0, -1, 0
	v_mbcnt_hi_u32_b32 v0, -1, v0
	v_or_b32_e32 v1, s24, v0
	v_lshl_add_u32 v2, s2, 9, v1
	s_mov_b32 s86, 0
	v_lshrrev_b32_e32 v3, 5, v2
	v_lshl_or_b32 v3, v3, 1, 1
	v_and_b32_e32 v4, 0x7ff, v3
	v_and_b32_e32 v5, 31, v2
	v_lshlrev_b32_e32 v5, 4, v5
	v_mul_u32_u24_e32 v6, 0x4800, v3
	v_add_u32_e32 v6, v6, v5
	v_lshl_add_u32 v7, v3, 11, v5
	v_mov_b32_e32 v16, v6
	v_mov_b32_e32 v33, 1.0
	v_cmp_le_u32_e32 vcc, 1, v4
	v_mov_b32_e32 v8, 0x4800
	s_nop 0
	v_cndmask_b32_e32 v8, 0, v8, vcc
	v_sub_u32_e32 v17, v6, v8
	v_cndmask_b32_e64 v34, 0, 1.0, vcc
	v_cmp_le_u32_e32 vcc, 2, v4
	v_mov_b32_e32 v8, 0x9000
	s_nop 0
	v_cndmask_b32_e32 v8, 0, v8, vcc
	v_sub_u32_e32 v18, v6, v8
	v_cndmask_b32_e64 v35, 0, 1.0, vcc
	v_cmp_le_u32_e32 vcc, 3, v4
	v_mov_b32_e32 v8, 0xd800
	s_nop 0
	v_cndmask_b32_e32 v8, 0, v8, vcc
	v_sub_u32_e32 v19, v6, v8
	v_cndmask_b32_e64 v36, 0, 1.0, vcc
	v_cmp_le_u32_e32 vcc, 4, v4
	v_mov_b32_e32 v8, 0x12000
	s_nop 0
	v_cndmask_b32_e32 v8, 0, v8, vcc
	v_sub_u32_e32 v20, v6, v8
	v_cndmask_b32_e64 v37, 0, 1.0, vcc
	v_cmp_le_u32_e32 vcc, 5, v4
	v_mov_b32_e32 v8, 0x16800
	s_nop 0
	v_cndmask_b32_e32 v8, 0, v8, vcc
	v_sub_u32_e32 v21, v6, v8
	v_cndmask_b32_e64 v38, 0, 1.0, vcc
	v_cmp_le_u32_e32 vcc, 6, v4
	v_mov_b32_e32 v8, 0x1b000
	s_nop 0
	v_cndmask_b32_e32 v8, 0, v8, vcc
	v_sub_u32_e32 v22, v6, v8
	v_cndmask_b32_e64 v39, 0, 1.0, vcc
	v_cmp_le_u32_e32 vcc, 7, v4
	v_mov_b32_e32 v8, 0x1f800
	s_nop 0
	v_cndmask_b32_e32 v8, 0, v8, vcc
	v_sub_u32_e32 v23, v6, v8
	v_cndmask_b32_e64 v40, 0, 1.0, vcc
	v_cmp_le_u32_e32 vcc, 8, v4
	v_mov_b32_e32 v8, 0x24000
	s_nop 0
	v_cndmask_b32_e32 v8, 0, v8, vcc
	v_sub_u32_e32 v24, v6, v8
	v_cndmask_b32_e64 v41, 0, 1.0, vcc
	v_cmp_le_u32_e32 vcc, 9, v4
	v_mov_b32_e32 v8, 0x28800
	s_nop 0
	v_cndmask_b32_e32 v8, 0, v8, vcc
	v_sub_u32_e32 v25, v6, v8
	v_cndmask_b32_e64 v42, 0, 1.0, vcc
	v_cmp_le_u32_e32 vcc, 10, v4
	v_mov_b32_e32 v8, 0x2d000
	s_nop 0
	v_cndmask_b32_e32 v8, 0, v8, vcc
	v_sub_u32_e32 v26, v6, v8
	v_cndmask_b32_e64 v43, 0, 1.0, vcc
	v_cmp_le_u32_e32 vcc, 11, v4
	v_mov_b32_e32 v8, 0x31800
	s_nop 0
	v_cndmask_b32_e32 v8, 0, v8, vcc
	v_sub_u32_e32 v27, v6, v8
	v_cndmask_b32_e64 v44, 0, 1.0, vcc
	v_cmp_le_u32_e32 vcc, 12, v4
	v_mov_b32_e32 v8, 0x36000
	s_nop 0
	v_cndmask_b32_e32 v8, 0, v8, vcc
	v_sub_u32_e32 v28, v6, v8
	v_cndmask_b32_e64 v45, 0, 1.0, vcc
	v_cmp_le_u32_e32 vcc, 13, v4
	v_mov_b32_e32 v8, 0x3a800
	s_nop 0
	v_cndmask_b32_e32 v8, 0, v8, vcc
	v_sub_u32_e32 v29, v6, v8
	v_cndmask_b32_e64 v46, 0, 1.0, vcc
	v_cmp_le_u32_e32 vcc, 14, v4
	v_mov_b32_e32 v8, 0x3f000
	s_nop 0
	v_cndmask_b32_e32 v8, 0, v8, vcc
	v_sub_u32_e32 v30, v6, v8
	v_cndmask_b32_e64 v47, 0, 1.0, vcc
	v_cmp_le_u32_e32 vcc, 15, v4
	v_mov_b32_e32 v8, 0x43800
	s_nop 0
	v_cndmask_b32_e32 v8, 0, v8, vcc
	v_sub_u32_e32 v31, v6, v8
	v_cndmask_b32_e64 v48, 0, 1.0, vcc
	v_cmp_le_u32_e32 vcc, 16, v4
	v_mov_b32_e32 v8, 0x48000
	s_nop 0
	v_cndmask_b32_e32 v8, 0, v8, vcc
	v_sub_u32_e32 v32, v6, v8
	v_cndmask_b32_e64 v49, 0, 1.0, vcc
	global_load_dwordx4 v[64:67], v16, s[28:29]
	global_load_dwordx4 v[68:71], v17, s[28:29]
	global_load_dwordx4 v[72:75], v18, s[28:29]
	global_load_dwordx4 v[76:79], v16, s[28:29] offset:512
	global_load_dwordx4 v[80:83], v17, s[28:29] offset:512
	global_load_dwordx4 v[84:87], v18, s[28:29] offset:512
	global_load_dwordx4 v[88:91], v19, s[28:29] offset:512
	global_load_dwordx4 v[92:95], v20, s[28:29] offset:512
	global_load_dwordx4 v[96:99], v16, s[28:29] offset:1024
	global_load_dwordx4 v[100:103], v17, s[28:29] offset:1024
	global_load_dwordx4 v[104:107], v18, s[28:29] offset:1024
	global_load_dwordx4 v[108:111], v19, s[28:29] offset:1024
	global_load_dwordx4 v[112:115], v20, s[28:29] offset:1024
	global_load_dwordx4 v[116:119], v21, s[28:29] offset:1024
	global_load_dwordx4 v[120:123], v22, s[28:29] offset:1024
	global_load_dwordx4 v[124:127], v23, s[28:29] offset:1024
	global_load_dwordx4 v[128:131], v24, s[28:29] offset:1024
	global_load_dwordx4 v[132:135], v16, s[28:29] offset:1536
	global_load_dwordx4 v[136:139], v17, s[28:29] offset:1536
	global_load_dwordx4 v[140:143], v18, s[28:29] offset:1536
	global_load_dwordx4 v[144:147], v19, s[28:29] offset:1536
	global_load_dwordx4 v[148:151], v20, s[28:29] offset:1536
	global_load_dwordx4 v[152:155], v21, s[28:29] offset:1536
	global_load_dwordx4 v[156:159], v22, s[28:29] offset:1536
	global_load_dwordx4 v[160:163], v23, s[28:29] offset:1536
	global_load_dwordx4 v[164:167], v24, s[28:29] offset:1536
	global_load_dwordx4 v[168:171], v25, s[28:29] offset:1536
	global_load_dwordx4 v[172:175], v26, s[28:29] offset:1536
	global_load_dwordx4 v[176:179], v27, s[28:29] offset:1536
	global_load_dwordx4 v[180:183], v28, s[28:29] offset:1536
	global_load_dwordx4 v[184:187], v29, s[28:29] offset:1536
	global_load_dwordx4 v[188:191], v30, s[28:29] offset:1536
	global_load_dwordx4 v[192:195], v31, s[28:29] offset:1536
	global_load_dwordx4 v[196:199], v32, s[28:29] offset:1536
	v_add_u32_e32 v9, 1, v4
	v_min_u32_e32 v10, 2, v9
	v_cvt_f32_u32_e32 v11, v10
	v_div_scale_f32 v200, s[88:89], v11, v11, 1.0
	v_rcp_f32_e32 v201, v200
	v_div_scale_f32 v202, vcc, 1.0, v11, 1.0
	v_fma_f32 v203, -v200, v201, 1.0
	v_fmac_f32_e32 v201, v203, v201
	v_mul_f32_e32 v203, v202, v201
	v_fma_f32 v204, -v200, v203, v202
	v_fmac_f32_e32 v203, v204, v201
; __device__ __forceinline__ unsigned pk2(float lo, float hi) { const f32x2_t v = {lo, hi}; const bf16x2_t b = __builtin_convertvector(v, bf16x2_t); return __builtin_bit_cast(unsigned, b); }
; template <int W>
; __device__ __forceinline__ void pool_item(const Params& p, const bf16_t* PROJ, bf16_t* D, int r, int c0) {
;     ...
;         const int t = r & 2047; cnt = (float)((t + 1 < W) ? (t + 1) : W);
;         u32x4 v[W - 1];
; #pragma unroll
;         for (int i = 1; i < W; ++i) v[i - 1] = *(const u32x4*)(PROJ + (size_t)(r - (i <= t ? i : 0)) * NQ + c0);
; #pragma unroll
;         for (int i = 1; i < W; ++i) acc8(sum, v[i - 1], (i <= t) ? 1.f : 0.f);
;     } else {
;         const int s = r - MP; cnt = (float)W; const float* sp = p.in[4] + (size_t)s * 15 * 1024 + c0;
;         f32x4 a[W - 1], b[W - 1];
; #pragma unroll
;         for (int i = 0; i < W - 1; ++i) { a[i] = *(const f32x4*)(sp + (size_t)(14 - i) * 1024); b[i] = *(const f32x4*)(sp + (size_t)(14 - i) * 1024 + 4); }
; #pragma unroll
;         for (int i = 0; i < W - 1; ++i) { sum[0] += a[i].x; sum[1] += a[i].y; sum[2] += a[i].z; sum[3] += a[i].w; sum[4] += b[i].x; sum[5] += b[i].y; sum[6] += b[i].z; sum[7] += b[i].w; }
;     }
;     const float inv = 1.0f / cnt; u32x4 o;
;     o.x = pk2(sum[0] * inv - uu[0], sum[1] * inv - uu[1]); o.y = pk2(sum[2] * inv - uu[2], sum[3] * inv - uu[3]);
;     o.z = pk2(sum[4] * inv - uu[4], sum[5] * inv - uu[5]); o.w = pk2(sum[6] * inv - uu[6], sum[7] * inv - uu[7]);
;     *(u32x4*)(D + (size_t)r * 1024 + c0) = o;
	v_fma_f32 v200, -v200, v203, v202
	v_div_fmas_f32 v200, v200, v201, v203
	v_div_fixup_f32 v50, v200, v11, 1.0
	v_min_u32_e32 v10, 2, v4
	v_cvt_f32_u32_e32 v11, v10
	v_div_scale_f32 v200, s[88:89], v11, v11, 1.0
	v_rcp_f32_e32 v201, v200
	v_div_scale_f32 v202, vcc, 1.0, v11, 1.0
	v_fma_f32 v203, -v200, v201, 1.0
	v_fmac_f32_e32 v201, v203, v201
	v_mul_f32_e32 v203, v202, v201
	v_fma_f32 v204, -v200, v203, v202
	v_fmac_f32_e32 v203, v204, v201
	v_fma_f32 v200, -v200, v203, v202
	v_div_fmas_f32 v200, v200, v201, v203
	v_div_fixup_f32 v54, v200, v11, 1.0
	v_min_u32_e32 v10, 4, v9
	v_cvt_f32_u32_e32 v11, v10
	v_div_scale_f32 v200, s[88:89], v11, v11, 1.0
	v_rcp_f32_e32 v201, v200
	v_div_scale_f32 v202, vcc, 1.0, v11, 1.0
	v_fma_f32 v203, -v200, v201, 1.0
	v_fmac_f32_e32 v201, v203, v201
	v_mul_f32_e32 v203, v202, v201
	v_fma_f32 v204, -v200, v203, v202
	v_fmac_f32_e32 v203, v204, v201
	v_fma_f32 v200, -v200, v203, v202
	v_div_fmas_f32 v200, v200, v201, v203
	v_div_fixup_f32 v51, v200, v11, 1.0
	v_min_u32_e32 v10, 4, v4
	v_cvt_f32_u32_e32 v11, v10
	v_div_scale_f32 v200, s[88:89], v11, v11, 1.0
	v_rcp_f32_e32 v201, v200
	v_div_scale_f32 v202, vcc, 1.0, v11, 1.0
	v_fma_f32 v203, -v200, v201, 1.0
	v_fmac_f32_e32 v201, v203, v201
	v_mul_f32_e32 v203, v202, v201
	v_fma_f32 v204, -v200, v203, v202
	v_fmac_f32_e32 v203, v204, v201
	v_fma_f32 v200, -v200, v203, v202
	v_div_fmas_f32 v200, v200, v201, v203
	v_div_fixup_f32 v55, v200, v11, 1.0
	v_min_u32_e32 v10, 8, v9
	v_cvt_f32_u32_e32 v11, v10
	v_div_scale_f32 v200, s[88:89], v11, v11, 1.0
	v_rcp_f32_e32 v201, v200
	v_div_scale_f32 v202, vcc, 1.0, v11, 1.0
	v_fma_f32 v203, -v200, v201, 1.0
	v_fmac_f32_e32 v201, v203, v201
	v_mul_f32_e32 v203, v202, v201
	v_fma_f32 v204, -v200, v203, v202
	v_fmac_f32_e32 v203, v204, v201
	v_fma_f32 v200, -v200, v203, v202
	v_div_fmas_f32 v200, v200, v201, v203
	v_div_fixup_f32 v52, v200, v11, 1.0
	v_min_u32_e32 v10, 8, v4
	v_cvt_f32_u32_e32 v11, v10
	v_div_scale_f32 v200, s[88:89], v11, v11, 1.0
	v_rcp_f32_e32 v201, v200
	v_div_scale_f32 v202, vcc, 1.0, v11, 1.0
	v_fma_f32 v203, -v200, v201, 1.0
	v_fmac_f32_e32 v201, v203, v201
	v_mul_f32_e32 v203, v202, v201
	v_fma_f32 v204, -v200, v203, v202
	v_fmac_f32_e32 v203, v204, v201
	v_fma_f32 v200, -v200, v203, v202
	v_div_fmas_f32 v200, v200, v201, v203
	v_div_fixup_f32 v56, v200, v11, 1.0
	v_min_u32_e32 v10, 16, v9
	v_cvt_f32_u32_e32 v11, v10
	v_div_scale_f32 v200, s[88:89], v11, v11, 1.0
	v_rcp_f32_e32 v201, v200
	v_div_scale_f32 v202, vcc, 1.0, v11, 1.0
	v_fma_f32 v203, -v200, v201, 1.0
	v_fmac_f32_e32 v201, v203, v201
	v_mul_f32_e32 v203, v202, v201
	v_fma_f32 v204, -v200, v203, v202
	v_fmac_f32_e32 v203, v204, v201
	v_fma_f32 v200, -v200, v203, v202
	v_div_fmas_f32 v200, v200, v201, v203
	v_div_fixup_f32 v53, v200, v11, 1.0
	v_min_u32_e32 v10, 16, v4
	v_cvt_f32_u32_e32 v11, v10
	v_div_scale_f32 v200, s[88:89], v11, v11, 1.0
	v_rcp_f32_e32 v201, v200
	v_div_scale_f32 v202, vcc, 1.0, v11, 1.0
	v_fma_f32 v203, -v200, v201, 1.0
	v_fmac_f32_e32 v201, v203, v201
	v_mul_f32_e32 v203, v202, v201
	v_fma_f32 v204, -v200, v203, v202
	v_fmac_f32_e32 v203, v204, v201
	v_fma_f32 v200, -v200, v203, v202
	v_div_fmas_f32 v200, v200, v201, v203
	v_div_fixup_f32 v57, v200, v11, 1.0
	s_waitcnt vmcnt(31)
	v_lshlrev_b32_e32 v206, 16, v64
	v_and_b32_e32 v207, 0xffff0000, v64
	v_lshlrev_b32_e32 v208, 16, v65
	v_and_b32_e32 v209, 0xffff0000, v65
	v_lshlrev_b32_e32 v210, 16, v66
	v_and_b32_e32 v211, 0xffff0000, v66
	v_lshlrev_b32_e32 v212, 16, v67
	v_and_b32_e32 v213, 0xffff0000, v67
	v_lshlrev_b32_e32 v214, 16, v68
	v_and_b32_e32 v215, 0xffff0000, v68
	v_lshlrev_b32_e32 v216, 16, v69
	v_and_b32_e32 v217, 0xffff0000, v69
	v_lshlrev_b32_e32 v218, 16, v70
	v_and_b32_e32 v219, 0xffff0000, v70
	v_lshlrev_b32_e32 v220, 16, v71
	v_and_b32_e32 v221, 0xffff0000, v71
	v_mov_b32_e32 v222, v206
	v_mov_b32_e32 v230, v214
	v_mov_b32_e32 v223, v207
	v_mov_b32_e32 v231, v215
	v_mov_b32_e32 v224, v208
	v_mov_b32_e32 v232, v216
	v_mov_b32_e32 v225, v209
	v_mov_b32_e32 v233, v217
	v_mov_b32_e32 v226, v210
	v_mov_b32_e32 v234, v218
	v_mov_b32_e32 v227, v211
	v_mov_b32_e32 v235, v219
	v_mov_b32_e32 v228, v212
	v_mov_b32_e32 v236, v220
	v_mov_b32_e32 v229, v213
	v_mov_b32_e32 v237, v221
	v_fmac_f32_e32 v222, v214, v34
	v_fmac_f32_e32 v223, v215, v34
	v_fmac_f32_e32 v224, v216, v34
	v_fmac_f32_e32 v225, v217, v34
	v_fmac_f32_e32 v226, v218, v34
	v_fmac_f32_e32 v227, v219, v34
	v_fmac_f32_e32 v228, v220, v34
	v_fmac_f32_e32 v229, v221, v34
	v_lshlrev_b32_e32 v238, 16, v72
	v_and_b32_e32 v239, 0xffff0000, v72
	v_lshlrev_b32_e32 v240, 16, v73
	v_and_b32_e32 v241, 0xffff0000, v73
	v_lshlrev_b32_e32 v242, 16, v74
	v_and_b32_e32 v243, 0xffff0000, v74
	v_lshlrev_b32_e32 v244, 16, v75
	v_and_b32_e32 v245, 0xffff0000, v75
	v_fmac_f32_e32 v230, v238, v35
	v_fmac_f32_e32 v231, v239, v35
	v_fmac_f32_e32 v232, v240, v35
	v_fmac_f32_e32 v233, v241, v35
	v_fmac_f32_e32 v234, v242, v35
	v_fmac_f32_e32 v235, v243, v35
	v_fmac_f32_e32 v236, v244, v35
	v_fmac_f32_e32 v237, v245, v35
	v_fma_f32 v222, v222, v50, -v206
	v_fma_f32 v230, v230, v54, -v214
	v_fma_f32 v223, v223, v50, -v207
	v_fma_f32 v231, v231, v54, -v215
	v_fma_f32 v224, v224, v50, -v208
	v_fma_f32 v232, v232, v54, -v216
	v_fma_f32 v225, v225, v50, -v209
	v_fma_f32 v233, v233, v54, -v217
	v_fma_f32 v226, v226, v50, -v210
	v_fma_f32 v234, v234, v54, -v218
	v_fma_f32 v227, v227, v50, -v211
	v_fma_f32 v235, v235, v54, -v219
	v_fma_f32 v228, v228, v50, -v212
	v_fma_f32 v236, v236, v54, -v220
	v_fma_f32 v229, v229, v50, -v213
	v_fma_f32 v237, v237, v54, -v221
	v_cvt_pk_bf16_f32 v246, v222, v223
	v_cvt_pk_bf16_f32 v247, v224, v225
	v_cvt_pk_bf16_f32 v248, v226, v227
	v_cvt_pk_bf16_f32 v249, v228, v229
	global_store_dwordx4 v7, v[246:249], s[84:85]
	s_nop 1
	v_cvt_pk_bf16_f32 v250, v230, v231
	v_cvt_pk_bf16_f32 v251, v232, v233
	v_cvt_pk_bf16_f32 v252, v234, v235
	v_cvt_pk_bf16_f32 v253, v236, v237
	global_store_dwordx4 v7, v[250:253], s[84:85] offset:-2048
	s_nop 1
	s_waitcnt vmcnt(28)
; __device__ __forceinline__ unsigned pk2(float lo, float hi) { const f32x2_t v = {lo, hi}; const bf16x2_t b = __builtin_convertvector(v, bf16x2_t); return __builtin_bit_cast(unsigned, b); }
; template <int W>
; __device__ __forceinline__ void pool_item(const Params& p, const bf16_t* PROJ, bf16_t* D, int r, int c0) {
;     ...
;         u32x4 v[W - 1];
; #pragma unroll
;         for (int i = 1; i < W; ++i) v[i - 1] = *(const u32x4*)(PROJ + (size_t)(r - (i <= t ? i : 0)) * NQ + c0);
; #pragma unroll
;         for (int i = 1; i < W; ++i) acc8(sum, v[i - 1], (i <= t) ? 1.f : 0.f);
;     } else {
;         const int s = r - MP; cnt = (float)W; const float* sp = p.in[4] + (size_t)s * 15 * 1024 + c0;
;         f32x4 a[W - 1], b[W - 1];
; #pragma unroll
;         for (int i = 0; i < W - 1; ++i) { a[i] = *(const f32x4*)(sp + (size_t)(14 - i) * 1024); b[i] = *(const f32x4*)(sp + (size_t)(14 - i) * 1024 + 4); }
; #pragma unroll
;         for (int i = 0; i < W - 1; ++i) { sum[0] += a[i].x; sum[1] += a[i].y; sum[2] += a[i].z; sum[3] += a[i].w; sum[4] += b[i].x; sum[5] += b[i].y; sum[6] += b[i].z; sum[7] += b[i].w; }
;     }
;     const float inv = 1.0f / cnt; u32x4 o;
;     o.x = pk2(sum[0] * inv - uu[0], sum[1] * inv - uu[1]); o.y = pk2(sum[2] * inv - uu[2], sum[3] * inv - uu[3]);
;     o.z = pk2(sum[4] * inv - uu[4], sum[5] * inv - uu[5]); o.w = pk2(sum[6] * inv - uu[6], sum[7] * inv - uu[7]);
;     *(u32x4*)(D + (size_t)r * 1024 + c0) = o;
	v_lshlrev_b32_e32 v206, 16, v76
	v_and_b32_e32 v207, 0xffff0000, v76
	v_lshlrev_b32_e32 v208, 16, v77
	v_and_b32_e32 v209, 0xffff0000, v77
	v_lshlrev_b32_e32 v210, 16, v78
	v_and_b32_e32 v211, 0xffff0000, v78
	v_lshlrev_b32_e32 v212, 16, v79
	v_and_b32_e32 v213, 0xffff0000, v79
	v_lshlrev_b32_e32 v214, 16, v80
	v_and_b32_e32 v215, 0xffff0000, v80
	v_lshlrev_b32_e32 v216, 16, v81
	v_and_b32_e32 v217, 0xffff0000, v81
	v_lshlrev_b32_e32 v218, 16, v82
	v_and_b32_e32 v219, 0xffff0000, v82
	v_lshlrev_b32_e32 v220, 16, v83
	v_and_b32_e32 v221, 0xffff0000, v83
	v_mov_b32_e32 v222, v206
	v_mov_b32_e32 v230, v214
	v_mov_b32_e32 v223, v207
	v_mov_b32_e32 v231, v215
	v_mov_b32_e32 v224, v208
	v_mov_b32_e32 v232, v216
	v_mov_b32_e32 v225, v209
	v_mov_b32_e32 v233, v217
	v_mov_b32_e32 v226, v210
	v_mov_b32_e32 v234, v218
	v_mov_b32_e32 v227, v211
	v_mov_b32_e32 v235, v219
	v_mov_b32_e32 v228, v212
	v_mov_b32_e32 v236, v220
	v_mov_b32_e32 v229, v213
	v_mov_b32_e32 v237, v221
	v_fmac_f32_e32 v222, v214, v34
	v_fmac_f32_e32 v223, v215, v34
	v_fmac_f32_e32 v224, v216, v34
	v_fmac_f32_e32 v225, v217, v34
	v_fmac_f32_e32 v226, v218, v34
	v_fmac_f32_e32 v227, v219, v34
	v_fmac_f32_e32 v228, v220, v34
	v_fmac_f32_e32 v229, v221, v34
	v_lshlrev_b32_e32 v238, 16, v84
	v_and_b32_e32 v239, 0xffff0000, v84
	v_lshlrev_b32_e32 v240, 16, v85
	v_and_b32_e32 v241, 0xffff0000, v85
	v_lshlrev_b32_e32 v242, 16, v86
	v_and_b32_e32 v243, 0xffff0000, v86
	v_lshlrev_b32_e32 v244, 16, v87
	v_and_b32_e32 v245, 0xffff0000, v87
	v_fmac_f32_e32 v222, v238, v35
	v_fmac_f32_e32 v230, v238, v35
	v_fmac_f32_e32 v223, v239, v35
	v_fmac_f32_e32 v231, v239, v35
	v_fmac_f32_e32 v224, v240, v35
	v_fmac_f32_e32 v232, v240, v35
	v_fmac_f32_e32 v225, v241, v35
	v_fmac_f32_e32 v233, v241, v35
	v_fmac_f32_e32 v226, v242, v35
	v_fmac_f32_e32 v234, v242, v35
	v_fmac_f32_e32 v227, v243, v35
	v_fmac_f32_e32 v235, v243, v35
	v_fmac_f32_e32 v228, v244, v35
	v_fmac_f32_e32 v236, v244, v35
	v_fmac_f32_e32 v229, v245, v35
	v_fmac_f32_e32 v237, v245, v35
	v_lshlrev_b32_e32 v238, 16, v88
	v_and_b32_e32 v239, 0xffff0000, v88
	v_lshlrev_b32_e32 v240, 16, v89
	v_and_b32_e32 v241, 0xffff0000, v89
	v_lshlrev_b32_e32 v242, 16, v90
	v_and_b32_e32 v243, 0xffff0000, v90
	v_lshlrev_b32_e32 v244, 16, v91
	v_and_b32_e32 v245, 0xffff0000, v91
	v_fmac_f32_e32 v222, v238, v36
	v_fmac_f32_e32 v230, v238, v36
	v_fmac_f32_e32 v223, v239, v36
	v_fmac_f32_e32 v231, v239, v36
	v_fmac_f32_e32 v224, v240, v36
	v_fmac_f32_e32 v232, v240, v36
	v_fmac_f32_e32 v225, v241, v36
	v_fmac_f32_e32 v233, v241, v36
	v_fmac_f32_e32 v226, v242, v36
	v_fmac_f32_e32 v234, v242, v36
	v_fmac_f32_e32 v227, v243, v36
	v_fmac_f32_e32 v235, v243, v36
	v_fmac_f32_e32 v228, v244, v36
	v_fmac_f32_e32 v236, v244, v36
	v_fmac_f32_e32 v229, v245, v36
	v_fmac_f32_e32 v237, v245, v36
	v_lshlrev_b32_e32 v238, 16, v92
	v_and_b32_e32 v239, 0xffff0000, v92
	v_lshlrev_b32_e32 v240, 16, v93
	v_and_b32_e32 v241, 0xffff0000, v93
	v_lshlrev_b32_e32 v242, 16, v94
	v_and_b32_e32 v243, 0xffff0000, v94
	v_lshlrev_b32_e32 v244, 16, v95
	v_and_b32_e32 v245, 0xffff0000, v95
	v_fmac_f32_e32 v230, v238, v37
	v_fmac_f32_e32 v231, v239, v37
	v_fmac_f32_e32 v232, v240, v37
	v_fmac_f32_e32 v233, v241, v37
	v_fmac_f32_e32 v234, v242, v37
	v_fmac_f32_e32 v235, v243, v37
	v_fmac_f32_e32 v236, v244, v37
	v_fmac_f32_e32 v237, v245, v37
	v_fma_f32 v222, v222, v51, -v206
	v_fma_f32 v230, v230, v55, -v214
	v_fma_f32 v223, v223, v51, -v207
	v_fma_f32 v231, v231, v55, -v215
	v_fma_f32 v224, v224, v51, -v208
	v_fma_f32 v232, v232, v55, -v216
	v_fma_f32 v225, v225, v51, -v209
	v_fma_f32 v233, v233, v55, -v217
	v_fma_f32 v226, v226, v51, -v210
	v_fma_f32 v234, v234, v55, -v218
	v_fma_f32 v227, v227, v51, -v211
	v_fma_f32 v235, v235, v55, -v219
	v_fma_f32 v228, v228, v51, -v212
	v_fma_f32 v236, v236, v55, -v220
	v_fma_f32 v229, v229, v51, -v213
	v_fma_f32 v237, v237, v55, -v221
	v_cvt_pk_bf16_f32 v246, v222, v223
	v_cvt_pk_bf16_f32 v247, v224, v225
	v_cvt_pk_bf16_f32 v248, v226, v227
	v_cvt_pk_bf16_f32 v249, v228, v229
	global_store_dwordx4 v7, v[246:249], s[84:85] offset:512
	s_nop 1
	v_cvt_pk_bf16_f32 v250, v230, v231
	v_cvt_pk_bf16_f32 v251, v232, v233
	v_cvt_pk_bf16_f32 v252, v234, v235
	v_cvt_pk_bf16_f32 v253, v236, v237
	global_store_dwordx4 v7, v[250:253], s[84:85] offset:-1536
	s_nop 1
	s_waitcnt vmcnt(21)
; template <int W>
; __device__ __forceinline__ void pool_item(const Params& p, const bf16_t* PROJ, bf16_t* D, int r, int c0) {
;     ...
;         u32x4 v[W - 1];
; #pragma unroll
;         for (int i = 1; i < W; ++i) v[i - 1] = *(const u32x4*)(PROJ + (size_t)(r - (i <= t ? i : 0)) * NQ + c0);
; #pragma unroll
;         for (int i = 1; i < W; ++i) acc8(sum, v[i - 1], (i <= t) ? 1.f : 0.f);
	v_lshlrev_b32_e32 v206, 16, v96
	v_and_b32_e32 v207, 0xffff0000, v96
	v_lshlrev_b32_e32 v208, 16, v97
	v_and_b32_e32 v209, 0xffff0000, v97
	v_lshlrev_b32_e32 v210, 16, v98
	v_and_b32_e32 v211, 0xffff0000, v98
	v_lshlrev_b32_e32 v212, 16, v99
	v_and_b32_e32 v213, 0xffff0000, v99
	v_lshlrev_b32_e32 v214, 16, v100
	v_and_b32_e32 v215, 0xffff0000, v100
	v_lshlrev_b32_e32 v216, 16, v101
	v_and_b32_e32 v217, 0xffff0000, v101
	v_lshlrev_b32_e32 v218, 16, v102
	v_and_b32_e32 v219, 0xffff0000, v102
	v_lshlrev_b32_e32 v220, 16, v103
	v_and_b32_e32 v221, 0xffff0000, v103
	v_mov_b32_e32 v222, v206
	v_mov_b32_e32 v230, v214
	v_mov_b32_e32 v223, v207
	v_mov_b32_e32 v231, v215
	v_mov_b32_e32 v224, v208
	v_mov_b32_e32 v232, v216
	v_mov_b32_e32 v225, v209
	v_mov_b32_e32 v233, v217
	v_mov_b32_e32 v226, v210
	v_mov_b32_e32 v234, v218
	v_mov_b32_e32 v227, v211
	v_mov_b32_e32 v235, v219
	v_mov_b32_e32 v228, v212
	v_mov_b32_e32 v236, v220
	v_mov_b32_e32 v229, v213
	v_mov_b32_e32 v237, v221
	v_fmac_f32_e32 v222, v214, v34
	v_fmac_f32_e32 v223, v215, v34
	v_fmac_f32_e32 v224, v216, v34
	v_fmac_f32_e32 v225, v217, v34
	v_fmac_f32_e32 v226, v218, v34
	v_fmac_f32_e32 v227, v219, v34
	v_fmac_f32_e32 v228, v220, v34
	v_fmac_f32_e32 v229, v221, v34
	v_lshlrev_b32_e32 v238, 16, v104
	v_and_b32_e32 v239, 0xffff0000, v104
	v_lshlrev_b32_e32 v240, 16, v105
	v_and_b32_e32 v241, 0xffff0000, v105
	v_lshlrev_b32_e32 v242, 16, v106
	v_and_b32_e32 v243, 0xffff0000, v106
	v_lshlrev_b32_e32 v244, 16, v107
	v_and_b32_e32 v245, 0xffff0000, v107
	v_fmac_f32_e32 v222, v238, v35
	v_fmac_f32_e32 v230, v238, v35
	v_fmac_f32_e32 v223, v239, v35
	v_fmac_f32_e32 v231, v239, v35
	v_fmac_f32_e32 v224, v240, v35
	v_fmac_f32_e32 v232, v240, v35
	v_fmac_f32_e32 v225, v241, v35
	v_fmac_f32_e32 v233, v241, v35
	v_fmac_f32_e32 v226, v242, v35
	v_fmac_f32_e32 v234, v242, v35
	v_fmac_f32_e32 v227, v243, v35
	v_fmac_f32_e32 v235, v243, v35
	v_fmac_f32_e32 v228, v244, v35
	v_fmac_f32_e32 v236, v244, v35
	v_fmac_f32_e32 v229, v245, v35
	v_fmac_f32_e32 v237, v245, v35
	v_lshlrev_b32_e32 v238, 16, v108
	v_and_b32_e32 v239, 0xffff0000, v108
	v_lshlrev_b32_e32 v240, 16, v109
	v_and_b32_e32 v241, 0xffff0000, v109
	v_lshlrev_b32_e32 v242, 16, v110
	v_and_b32_e32 v243, 0xffff0000, v110
	v_lshlrev_b32_e32 v244, 16, v111
	v_and_b32_e32 v245, 0xffff0000, v111
	v_fmac_f32_e32 v222, v238, v36
	v_fmac_f32_e32 v230, v238, v36
	v_fmac_f32_e32 v223, v239, v36
	v_fmac_f32_e32 v231, v239, v36
	v_fmac_f32_e32 v224, v240, v36
	v_fmac_f32_e32 v232, v240, v36
	v_fmac_f32_e32 v225, v241, v36
	v_fmac_f32_e32 v233, v241, v36
	v_fmac_f32_e32 v226, v242, v36
	v_fmac_f32_e32 v234, v242, v36
	v_fmac_f32_e32 v227, v243, v36
	v_fmac_f32_e32 v235, v243, v36
	v_fmac_f32_e32 v228, v244, v36
	v_fmac_f32_e32 v236, v244, v36
	v_fmac_f32_e32 v229, v245, v36
	v_fmac_f32_e32 v237, v245, v36
	v_lshlrev_b32_e32 v238, 16, v112
	v_and_b32_e32 v239, 0xffff0000, v112
	v_lshlrev_b32_e32 v240, 16, v113
	v_and_b32_e32 v241, 0xffff0000, v113
	v_lshlrev_b32_e32 v242, 16, v114
	v_and_b32_e32 v243, 0xffff0000, v114
	v_lshlrev_b32_e32 v244, 16, v115
	v_and_b32_e32 v245, 0xffff0000, v115
	v_fmac_f32_e32 v222, v238, v37
	v_fmac_f32_e32 v230, v238, v37
	v_fmac_f32_e32 v223, v239, v37
	v_fmac_f32_e32 v231, v239, v37
	v_fmac_f32_e32 v224, v240, v37
	v_fmac_f32_e32 v232, v240, v37
	v_fmac_f32_e32 v225, v241, v37
	v_fmac_f32_e32 v233, v241, v37
	v_fmac_f32_e32 v226, v242, v37
	v_fmac_f32_e32 v234, v242, v37
	v_fmac_f32_e32 v227, v243, v37
	v_fmac_f32_e32 v235, v243, v37
	v_fmac_f32_e32 v228, v244, v37
	v_fmac_f32_e32 v236, v244, v37
	v_fmac_f32_e32 v229, v245, v37
	v_fmac_f32_e32 v237, v245, v37
	v_lshlrev_b32_e32 v238, 16, v116
	v_and_b32_e32 v239, 0xffff0000, v116
	v_lshlrev_b32_e32 v240, 16, v117
	v_and_b32_e32 v241, 0xffff0000, v117
	v_lshlrev_b32_e32 v242, 16, v118
	v_and_b32_e32 v243, 0xffff0000, v118
	v_lshlrev_b32_e32 v244, 16, v119
	v_and_b32_e32 v245, 0xffff0000, v119
	v_fmac_f32_e32 v222, v238, v38
	v_fmac_f32_e32 v230, v238, v38
	v_fmac_f32_e32 v223, v239, v38
	v_fmac_f32_e32 v231, v239, v38
	v_fmac_f32_e32 v224, v240, v38
	v_fmac_f32_e32 v232, v240, v38
	v_fmac_f32_e32 v225, v241, v38
	v_fmac_f32_e32 v233, v241, v38
	v_fmac_f32_e32 v226, v242, v38
	v_fmac_f32_e32 v234, v242, v38
	v_fmac_f32_e32 v227, v243, v38
	v_fmac_f32_e32 v235, v243, v38
	v_fmac_f32_e32 v228, v244, v38
	v_fmac_f32_e32 v236, v244, v38
	v_fmac_f32_e32 v229, v245, v38
	v_fmac_f32_e32 v237, v245, v38
	v_lshlrev_b32_e32 v238, 16, v120
	v_and_b32_e32 v239, 0xffff0000, v120
	v_lshlrev_b32_e32 v240, 16, v121
	v_and_b32_e32 v241, 0xffff0000, v121
	v_lshlrev_b32_e32 v242, 16, v122
	v_and_b32_e32 v243, 0xffff0000, v122
	v_lshlrev_b32_e32 v244, 16, v123
	v_and_b32_e32 v245, 0xffff0000, v123
	v_fmac_f32_e32 v222, v238, v39
	v_fmac_f32_e32 v230, v238, v39
	v_fmac_f32_e32 v223, v239, v39
	v_fmac_f32_e32 v231, v239, v39
	v_fmac_f32_e32 v224, v240, v39
	v_fmac_f32_e32 v232, v240, v39
	v_fmac_f32_e32 v225, v241, v39
	v_fmac_f32_e32 v233, v241, v39
	v_fmac_f32_e32 v226, v242, v39
	v_fmac_f32_e32 v234, v242, v39
	v_fmac_f32_e32 v227, v243, v39
	v_fmac_f32_e32 v235, v243, v39
	v_fmac_f32_e32 v228, v244, v39
	v_fmac_f32_e32 v236, v244, v39
	v_fmac_f32_e32 v229, v245, v39
	v_fmac_f32_e32 v237, v245, v39
	v_lshlrev_b32_e32 v238, 16, v124
	v_and_b32_e32 v239, 0xffff0000, v124
	v_lshlrev_b32_e32 v240, 16, v125
	v_and_b32_e32 v241, 0xffff0000, v125
	v_lshlrev_b32_e32 v242, 16, v126
	v_and_b32_e32 v243, 0xffff0000, v126
	v_lshlrev_b32_e32 v244, 16, v127
	v_and_b32_e32 v245, 0xffff0000, v127
	v_fmac_f32_e32 v222, v238, v40
	v_fmac_f32_e32 v230, v238, v40
	v_fmac_f32_e32 v223, v239, v40
; __device__ __forceinline__ unsigned pk2(float lo, float hi) { const f32x2_t v = {lo, hi}; const bf16x2_t b = __builtin_convertvector(v, bf16x2_t); return __builtin_bit_cast(unsigned, b); }
; template <int W>
; __device__ __forceinline__ void pool_item(const Params& p, const bf16_t* PROJ, bf16_t* D, int r, int c0) {
;     ...
;         u32x4 v[W - 1];
; #pragma unroll
;         for (int i = 1; i < W; ++i) v[i - 1] = *(const u32x4*)(PROJ + (size_t)(r - (i <= t ? i : 0)) * NQ + c0);
; #pragma unroll
;         for (int i = 1; i < W; ++i) acc8(sum, v[i - 1], (i <= t) ? 1.f : 0.f);
;     } else {
;         const int s = r - MP; cnt = (float)W; const float* sp = p.in[4] + (size_t)s * 15 * 1024 + c0;
;         f32x4 a[W - 1], b[W - 1];
; #pragma unroll
;         for (int i = 0; i < W - 1; ++i) { a[i] = *(const f32x4*)(sp + (size_t)(14 - i) * 1024); b[i] = *(const f32x4*)(sp + (size_t)(14 - i) * 1024 + 4); }
; #pragma unroll
;         for (int i = 0; i < W - 1; ++i) { sum[0] += a[i].x; sum[1] += a[i].y; sum[2] += a[i].z; sum[3] += a[i].w; sum[4] += b[i].x; sum[5] += b[i].y; sum[6] += b[i].z; sum[7] += b[i].w; }
;     }
;     const float inv = 1.0f / cnt; u32x4 o;
;     o.x = pk2(sum[0] * inv - uu[0], sum[1] * inv - uu[1]); o.y = pk2(sum[2] * inv - uu[2], sum[3] * inv - uu[3]);
;     o.z = pk2(sum[4] * inv - uu[4], sum[5] * inv - uu[5]); o.w = pk2(sum[6] * inv - uu[6], sum[7] * inv - uu[7]);
;     *(u32x4*)(D + (size_t)r * 1024 + c0) = o;
	v_fmac_f32_e32 v231, v239, v40
	v_fmac_f32_e32 v224, v240, v40
	v_fmac_f32_e32 v232, v240, v40
	v_fmac_f32_e32 v225, v241, v40
	v_fmac_f32_e32 v233, v241, v40
	v_fmac_f32_e32 v226, v242, v40
	v_fmac_f32_e32 v234, v242, v40
	v_fmac_f32_e32 v227, v243, v40
	v_fmac_f32_e32 v235, v243, v40
	v_fmac_f32_e32 v228, v244, v40
	v_fmac_f32_e32 v236, v244, v40
	v_fmac_f32_e32 v229, v245, v40
	v_fmac_f32_e32 v237, v245, v40
	v_lshlrev_b32_e32 v238, 16, v128
	v_and_b32_e32 v239, 0xffff0000, v128
	v_lshlrev_b32_e32 v240, 16, v129
	v_and_b32_e32 v241, 0xffff0000, v129
	v_lshlrev_b32_e32 v242, 16, v130
	v_and_b32_e32 v243, 0xffff0000, v130
	v_lshlrev_b32_e32 v244, 16, v131
	v_and_b32_e32 v245, 0xffff0000, v131
	v_fmac_f32_e32 v230, v238, v41
	v_fmac_f32_e32 v231, v239, v41
	v_fmac_f32_e32 v232, v240, v41
	v_fmac_f32_e32 v233, v241, v41
	v_fmac_f32_e32 v234, v242, v41
	v_fmac_f32_e32 v235, v243, v41
	v_fmac_f32_e32 v236, v244, v41
	v_fmac_f32_e32 v237, v245, v41
	v_fma_f32 v222, v222, v52, -v206
	v_fma_f32 v230, v230, v56, -v214
	v_fma_f32 v223, v223, v52, -v207
	v_fma_f32 v231, v231, v56, -v215
	v_fma_f32 v224, v224, v52, -v208
	v_fma_f32 v232, v232, v56, -v216
	v_fma_f32 v225, v225, v52, -v209
	v_fma_f32 v233, v233, v56, -v217
	v_fma_f32 v226, v226, v52, -v210
	v_fma_f32 v234, v234, v56, -v218
	v_fma_f32 v227, v227, v52, -v211
	v_fma_f32 v235, v235, v56, -v219
	v_fma_f32 v228, v228, v52, -v212
	v_fma_f32 v236, v236, v56, -v220
	v_fma_f32 v229, v229, v52, -v213
	v_fma_f32 v237, v237, v56, -v221
	v_cvt_pk_bf16_f32 v246, v222, v223
	v_cvt_pk_bf16_f32 v247, v224, v225
	v_cvt_pk_bf16_f32 v248, v226, v227
	v_cvt_pk_bf16_f32 v249, v228, v229
	global_store_dwordx4 v7, v[246:249], s[84:85] offset:1024
	s_nop 1
	v_cvt_pk_bf16_f32 v250, v230, v231
	v_cvt_pk_bf16_f32 v251, v232, v233
	v_cvt_pk_bf16_f32 v252, v234, v235
	v_cvt_pk_bf16_f32 v253, v236, v237
	global_store_dwordx4 v7, v[250:253], s[84:85] offset:-1024
	s_nop 1
	s_waitcnt vmcnt(6)
	v_lshlrev_b32_e32 v206, 16, v132
	v_and_b32_e32 v207, 0xffff0000, v132
	v_lshlrev_b32_e32 v208, 16, v133
	v_and_b32_e32 v209, 0xffff0000, v133
	v_lshlrev_b32_e32 v210, 16, v134
	v_and_b32_e32 v211, 0xffff0000, v134
	v_lshlrev_b32_e32 v212, 16, v135
	v_and_b32_e32 v213, 0xffff0000, v135
	v_lshlrev_b32_e32 v214, 16, v136
	v_and_b32_e32 v215, 0xffff0000, v136
	v_lshlrev_b32_e32 v216, 16, v137
	v_and_b32_e32 v217, 0xffff0000, v137
	v_lshlrev_b32_e32 v218, 16, v138
	v_and_b32_e32 v219, 0xffff0000, v138
	v_lshlrev_b32_e32 v220, 16, v139
	v_and_b32_e32 v221, 0xffff0000, v139
	v_mov_b32_e32 v222, v206
	v_mov_b32_e32 v230, v214
	v_mov_b32_e32 v223, v207
	v_mov_b32_e32 v231, v215
	v_mov_b32_e32 v224, v208
	v_mov_b32_e32 v232, v216
	v_mov_b32_e32 v225, v209
	v_mov_b32_e32 v233, v217
	v_mov_b32_e32 v226, v210
	v_mov_b32_e32 v234, v218
	v_mov_b32_e32 v227, v211
	v_mov_b32_e32 v235, v219
	v_mov_b32_e32 v228, v212
	v_mov_b32_e32 v236, v220
	v_mov_b32_e32 v229, v213
	v_mov_b32_e32 v237, v221
	v_fmac_f32_e32 v222, v214, v34
	v_fmac_f32_e32 v223, v215, v34
	v_fmac_f32_e32 v224, v216, v34
	v_fmac_f32_e32 v225, v217, v34
	v_fmac_f32_e32 v226, v218, v34
	v_fmac_f32_e32 v227, v219, v34
	v_fmac_f32_e32 v228, v220, v34
	v_fmac_f32_e32 v229, v221, v34
	v_lshlrev_b32_e32 v238, 16, v140
	v_and_b32_e32 v239, 0xffff0000, v140
	v_lshlrev_b32_e32 v240, 16, v141
	v_and_b32_e32 v241, 0xffff0000, v141
	v_lshlrev_b32_e32 v242, 16, v142
	v_and_b32_e32 v243, 0xffff0000, v142
	v_lshlrev_b32_e32 v244, 16, v143
	v_and_b32_e32 v245, 0xffff0000, v143
	v_fmac_f32_e32 v222, v238, v35
	v_fmac_f32_e32 v230, v238, v35
	v_fmac_f32_e32 v223, v239, v35
	v_fmac_f32_e32 v231, v239, v35
	v_fmac_f32_e32 v224, v240, v35
	v_fmac_f32_e32 v232, v240, v35
	v_fmac_f32_e32 v225, v241, v35
	v_fmac_f32_e32 v233, v241, v35
	v_fmac_f32_e32 v226, v242, v35
	v_fmac_f32_e32 v234, v242, v35
	v_fmac_f32_e32 v227, v243, v35
	v_fmac_f32_e32 v235, v243, v35
	v_fmac_f32_e32 v228, v244, v35
	v_fmac_f32_e32 v236, v244, v35
	v_fmac_f32_e32 v229, v245, v35
	v_fmac_f32_e32 v237, v245, v35
	v_lshlrev_b32_e32 v238, 16, v144
	v_and_b32_e32 v239, 0xffff0000, v144
	v_lshlrev_b32_e32 v240, 16, v145
	v_and_b32_e32 v241, 0xffff0000, v145
	v_lshlrev_b32_e32 v242, 16, v146
	v_and_b32_e32 v243, 0xffff0000, v146
	v_lshlrev_b32_e32 v244, 16, v147
	v_and_b32_e32 v245, 0xffff0000, v147
	v_fmac_f32_e32 v222, v238, v36
	v_fmac_f32_e32 v230, v238, v36
	v_fmac_f32_e32 v223, v239, v36
	v_fmac_f32_e32 v231, v239, v36
	v_fmac_f32_e32 v224, v240, v36
	v_fmac_f32_e32 v232, v240, v36
	v_fmac_f32_e32 v225, v241, v36
	v_fmac_f32_e32 v233, v241, v36
	v_fmac_f32_e32 v226, v242, v36
	v_fmac_f32_e32 v234, v242, v36
	v_fmac_f32_e32 v227, v243, v36
	v_fmac_f32_e32 v235, v243, v36
	v_fmac_f32_e32 v228, v244, v36
	v_fmac_f32_e32 v236, v244, v36
	v_fmac_f32_e32 v229, v245, v36
	v_fmac_f32_e32 v237, v245, v36
	v_lshlrev_b32_e32 v238, 16, v148
	v_and_b32_e32 v239, 0xffff0000, v148
	v_lshlrev_b32_e32 v240, 16, v149
	v_and_b32_e32 v241, 0xffff0000, v149
	v_lshlrev_b32_e32 v242, 16, v150
	v_and_b32_e32 v243, 0xffff0000, v150
	v_lshlrev_b32_e32 v244, 16, v151
	v_and_b32_e32 v245, 0xffff0000, v151
	v_fmac_f32_e32 v222, v238, v37
	v_fmac_f32_e32 v230, v238, v37
	v_fmac_f32_e32 v223, v239, v37
	v_fmac_f32_e32 v231, v239, v37
	v_fmac_f32_e32 v224, v240, v37
	v_fmac_f32_e32 v232, v240, v37
	v_fmac_f32_e32 v225, v241, v37
	v_fmac_f32_e32 v233, v241, v37
	v_fmac_f32_e32 v226, v242, v37
	v_fmac_f32_e32 v234, v242, v37
	v_fmac_f32_e32 v227, v243, v37
	v_fmac_f32_e32 v235, v243, v37
	v_fmac_f32_e32 v228, v244, v37
	v_fmac_f32_e32 v236, v244, v37
	v_fmac_f32_e32 v229, v245, v37
	v_fmac_f32_e32 v237, v245, v37
	v_lshlrev_b32_e32 v238, 16, v152
; template <int W>
; __device__ __forceinline__ void pool_item(const Params& p, const bf16_t* PROJ, bf16_t* D, int r, int c0) {
;     ...
;         for (int i = 1; i < W; ++i) v[i - 1] = *(const u32x4*)(PROJ + (size_t)(r - (i <= t ? i : 0)) * NQ + c0);
; #pragma unroll
;         for (int i = 1; i < W; ++i) acc8(sum, v[i - 1], (i <= t) ? 1.f : 0.f);
	v_and_b32_e32 v239, 0xffff0000, v152
	v_lshlrev_b32_e32 v240, 16, v153
	v_and_b32_e32 v241, 0xffff0000, v153
	v_lshlrev_b32_e32 v242, 16, v154
	v_and_b32_e32 v243, 0xffff0000, v154
	v_lshlrev_b32_e32 v244, 16, v155
	v_and_b32_e32 v245, 0xffff0000, v155
	v_fmac_f32_e32 v222, v238, v38
	v_fmac_f32_e32 v230, v238, v38
	v_fmac_f32_e32 v223, v239, v38
	v_fmac_f32_e32 v231, v239, v38
	v_fmac_f32_e32 v224, v240, v38
	v_fmac_f32_e32 v232, v240, v38
	v_fmac_f32_e32 v225, v241, v38
	v_fmac_f32_e32 v233, v241, v38
	v_fmac_f32_e32 v226, v242, v38
	v_fmac_f32_e32 v234, v242, v38
	v_fmac_f32_e32 v227, v243, v38
	v_fmac_f32_e32 v235, v243, v38
	v_fmac_f32_e32 v228, v244, v38
	v_fmac_f32_e32 v236, v244, v38
	v_fmac_f32_e32 v229, v245, v38
	v_fmac_f32_e32 v237, v245, v38
	v_lshlrev_b32_e32 v238, 16, v156
	v_and_b32_e32 v239, 0xffff0000, v156
	v_lshlrev_b32_e32 v240, 16, v157
	v_and_b32_e32 v241, 0xffff0000, v157
	v_lshlrev_b32_e32 v242, 16, v158
	v_and_b32_e32 v243, 0xffff0000, v158
	v_lshlrev_b32_e32 v244, 16, v159
	v_and_b32_e32 v245, 0xffff0000, v159
	v_fmac_f32_e32 v222, v238, v39
	v_fmac_f32_e32 v230, v238, v39
	v_fmac_f32_e32 v223, v239, v39
	v_fmac_f32_e32 v231, v239, v39
	v_fmac_f32_e32 v224, v240, v39
	v_fmac_f32_e32 v232, v240, v39
	v_fmac_f32_e32 v225, v241, v39
	v_fmac_f32_e32 v233, v241, v39
	v_fmac_f32_e32 v226, v242, v39
	v_fmac_f32_e32 v234, v242, v39
	v_fmac_f32_e32 v227, v243, v39
	v_fmac_f32_e32 v235, v243, v39
	v_fmac_f32_e32 v228, v244, v39
	v_fmac_f32_e32 v236, v244, v39
	v_fmac_f32_e32 v229, v245, v39
	v_fmac_f32_e32 v237, v245, v39
	v_lshlrev_b32_e32 v238, 16, v160
	v_and_b32_e32 v239, 0xffff0000, v160
	v_lshlrev_b32_e32 v240, 16, v161
	v_and_b32_e32 v241, 0xffff0000, v161
	v_lshlrev_b32_e32 v242, 16, v162
	v_and_b32_e32 v243, 0xffff0000, v162
	v_lshlrev_b32_e32 v244, 16, v163
	v_and_b32_e32 v245, 0xffff0000, v163
	v_fmac_f32_e32 v222, v238, v40
	v_fmac_f32_e32 v230, v238, v40
	v_fmac_f32_e32 v223, v239, v40
	v_fmac_f32_e32 v231, v239, v40
	v_fmac_f32_e32 v224, v240, v40
	v_fmac_f32_e32 v232, v240, v40
	v_fmac_f32_e32 v225, v241, v40
	v_fmac_f32_e32 v233, v241, v40
	v_fmac_f32_e32 v226, v242, v40
	v_fmac_f32_e32 v234, v242, v40
	v_fmac_f32_e32 v227, v243, v40
	v_fmac_f32_e32 v235, v243, v40
	v_fmac_f32_e32 v228, v244, v40
	v_fmac_f32_e32 v236, v244, v40
	v_fmac_f32_e32 v229, v245, v40
	v_fmac_f32_e32 v237, v245, v40
	v_lshlrev_b32_e32 v238, 16, v164
	v_and_b32_e32 v239, 0xffff0000, v164
	v_lshlrev_b32_e32 v240, 16, v165
	v_and_b32_e32 v241, 0xffff0000, v165
	v_lshlrev_b32_e32 v242, 16, v166
	v_and_b32_e32 v243, 0xffff0000, v166
	v_lshlrev_b32_e32 v244, 16, v167
	v_and_b32_e32 v245, 0xffff0000, v167
	v_fmac_f32_e32 v222, v238, v41
	v_fmac_f32_e32 v230, v238, v41
	v_fmac_f32_e32 v223, v239, v41
	v_fmac_f32_e32 v231, v239, v41
	v_fmac_f32_e32 v224, v240, v41
	v_fmac_f32_e32 v232, v240, v41
	v_fmac_f32_e32 v225, v241, v41
	v_fmac_f32_e32 v233, v241, v41
	v_fmac_f32_e32 v226, v242, v41
	v_fmac_f32_e32 v234, v242, v41
	v_fmac_f32_e32 v227, v243, v41
	v_fmac_f32_e32 v235, v243, v41
	v_fmac_f32_e32 v228, v244, v41
	v_fmac_f32_e32 v236, v244, v41
	v_fmac_f32_e32 v229, v245, v41
	v_fmac_f32_e32 v237, v245, v41
	v_lshlrev_b32_e32 v238, 16, v168
	v_and_b32_e32 v239, 0xffff0000, v168
	v_lshlrev_b32_e32 v240, 16, v169
	v_and_b32_e32 v241, 0xffff0000, v169
	v_lshlrev_b32_e32 v242, 16, v170
	v_and_b32_e32 v243, 0xffff0000, v170
	v_lshlrev_b32_e32 v244, 16, v171
	v_and_b32_e32 v245, 0xffff0000, v171
	v_fmac_f32_e32 v222, v238, v42
	v_fmac_f32_e32 v230, v238, v42
	v_fmac_f32_e32 v223, v239, v42
	v_fmac_f32_e32 v231, v239, v42
	v_fmac_f32_e32 v224, v240, v42
	v_fmac_f32_e32 v232, v240, v42
	v_fmac_f32_e32 v225, v241, v42
	v_fmac_f32_e32 v233, v241, v42
	v_fmac_f32_e32 v226, v242, v42
	v_fmac_f32_e32 v234, v242, v42
	v_fmac_f32_e32 v227, v243, v42
	v_fmac_f32_e32 v235, v243, v42
	v_fmac_f32_e32 v228, v244, v42
	v_fmac_f32_e32 v236, v244, v42
	v_fmac_f32_e32 v229, v245, v42
	v_fmac_f32_e32 v237, v245, v42
	v_lshlrev_b32_e32 v238, 16, v172
	v_and_b32_e32 v239, 0xffff0000, v172
	v_lshlrev_b32_e32 v240, 16, v173
	v_and_b32_e32 v241, 0xffff0000, v173
	v_lshlrev_b32_e32 v242, 16, v174
	v_and_b32_e32 v243, 0xffff0000, v174
	v_lshlrev_b32_e32 v244, 16, v175
	v_and_b32_e32 v245, 0xffff0000, v175
	v_fmac_f32_e32 v222, v238, v43
	v_fmac_f32_e32 v230, v238, v43
	v_fmac_f32_e32 v223, v239, v43
	v_fmac_f32_e32 v231, v239, v43
	v_fmac_f32_e32 v224, v240, v43
	v_fmac_f32_e32 v232, v240, v43
	v_fmac_f32_e32 v225, v241, v43
	v_fmac_f32_e32 v233, v241, v43
	v_fmac_f32_e32 v226, v242, v43
	v_fmac_f32_e32 v234, v242, v43
	v_fmac_f32_e32 v227, v243, v43
	v_fmac_f32_e32 v235, v243, v43
	v_fmac_f32_e32 v228, v244, v43
	v_fmac_f32_e32 v236, v244, v43
	v_fmac_f32_e32 v229, v245, v43
	v_fmac_f32_e32 v237, v245, v43
	v_lshlrev_b32_e32 v238, 16, v176
	v_and_b32_e32 v239, 0xffff0000, v176
	v_lshlrev_b32_e32 v240, 16, v177
	v_and_b32_e32 v241, 0xffff0000, v177
	v_lshlrev_b32_e32 v242, 16, v178
	v_and_b32_e32 v243, 0xffff0000, v178
	v_lshlrev_b32_e32 v244, 16, v179
	v_and_b32_e32 v245, 0xffff0000, v179
	v_fmac_f32_e32 v222, v238, v44
	v_fmac_f32_e32 v230, v238, v44
	v_fmac_f32_e32 v223, v239, v44
	v_fmac_f32_e32 v231, v239, v44
	v_fmac_f32_e32 v224, v240, v44
	v_fmac_f32_e32 v232, v240, v44
	v_fmac_f32_e32 v225, v241, v44
	v_fmac_f32_e32 v233, v241, v44
	v_fmac_f32_e32 v226, v242, v44
	v_fmac_f32_e32 v234, v242, v44
	v_fmac_f32_e32 v227, v243, v44
	v_fmac_f32_e32 v235, v243, v44
	v_fmac_f32_e32 v228, v244, v44
	v_fmac_f32_e32 v236, v244, v44
	v_fmac_f32_e32 v229, v245, v44
	v_fmac_f32_e32 v237, v245, v44
	v_lshlrev_b32_e32 v238, 16, v180
	v_and_b32_e32 v239, 0xffff0000, v180
; __device__ __forceinline__ unsigned pk2(float lo, float hi) { const f32x2_t v = {lo, hi}; const bf16x2_t b = __builtin_convertvector(v, bf16x2_t); return __builtin_bit_cast(unsigned, b); }
; template <int W>
; __device__ __forceinline__ void pool_item(const Params& p, const bf16_t* PROJ, bf16_t* D, int r, int c0) {
;     ...
;         for (int i = 1; i < W; ++i) v[i - 1] = *(const u32x4*)(PROJ + (size_t)(r - (i <= t ? i : 0)) * NQ + c0);
; #pragma unroll
;         for (int i = 1; i < W; ++i) acc8(sum, v[i - 1], (i <= t) ? 1.f : 0.f);
;     } else {
;         const int s = r - MP; cnt = (float)W; const float* sp = p.in[4] + (size_t)s * 15 * 1024 + c0;
;         f32x4 a[W - 1], b[W - 1];
; #pragma unroll
;         for (int i = 0; i < W - 1; ++i) { a[i] = *(const f32x4*)(sp + (size_t)(14 - i) * 1024); b[i] = *(const f32x4*)(sp + (size_t)(14 - i) * 1024 + 4); }
; #pragma unroll
;         for (int i = 0; i < W - 1; ++i) { sum[0] += a[i].x; sum[1] += a[i].y; sum[2] += a[i].z; sum[3] += a[i].w; sum[4] += b[i].x; sum[5] += b[i].y; sum[6] += b[i].z; sum[7] += b[i].w; }
;     }
;     const float inv = 1.0f / cnt; u32x4 o;
;     o.x = pk2(sum[0] * inv - uu[0], sum[1] * inv - uu[1]); o.y = pk2(sum[2] * inv - uu[2], sum[3] * inv - uu[3]);
;     o.z = pk2(sum[4] * inv - uu[4], sum[5] * inv - uu[5]); o.w = pk2(sum[6] * inv - uu[6], sum[7] * inv - uu[7]);
;     *(u32x4*)(D + (size_t)r * 1024 + c0) = o;
; __device__ __forceinline__ void phase_pool_d(const Params& p, int wave_s) {
;     ...
;     for (int idx = blockIdx.x * 512 + tid; idx < total; idx += gridDim.x * 512) {
;         const int r = idx >> 5, ch = idx & 31;
;         pool_item<2>(p, PROJ, D, r, ch * 8);
;         pool_item<4>(p, PROJ, D, r, 256 + ch * 8);
;         pool_item<8>(p, PROJ, D, r, 512 + ch * 8);
;         pool_item<16>(p, PROJ, D, r, 768 + ch * 8);
;     }
	v_lshlrev_b32_e32 v240, 16, v181
	v_and_b32_e32 v241, 0xffff0000, v181
	v_lshlrev_b32_e32 v242, 16, v182
	v_and_b32_e32 v243, 0xffff0000, v182
	v_lshlrev_b32_e32 v244, 16, v183
	v_and_b32_e32 v245, 0xffff0000, v183
	v_fmac_f32_e32 v222, v238, v45
	v_fmac_f32_e32 v230, v238, v45
	v_fmac_f32_e32 v223, v239, v45
	v_fmac_f32_e32 v231, v239, v45
	v_fmac_f32_e32 v224, v240, v45
	v_fmac_f32_e32 v232, v240, v45
	v_fmac_f32_e32 v225, v241, v45
	v_fmac_f32_e32 v233, v241, v45
	v_fmac_f32_e32 v226, v242, v45
	v_fmac_f32_e32 v234, v242, v45
	v_fmac_f32_e32 v227, v243, v45
	v_fmac_f32_e32 v235, v243, v45
	v_fmac_f32_e32 v228, v244, v45
	v_fmac_f32_e32 v236, v244, v45
	v_fmac_f32_e32 v229, v245, v45
	v_fmac_f32_e32 v237, v245, v45
	v_lshlrev_b32_e32 v238, 16, v184
	v_and_b32_e32 v239, 0xffff0000, v184
	v_lshlrev_b32_e32 v240, 16, v185
	v_and_b32_e32 v241, 0xffff0000, v185
	v_lshlrev_b32_e32 v242, 16, v186
	v_and_b32_e32 v243, 0xffff0000, v186
	v_lshlrev_b32_e32 v244, 16, v187
	v_and_b32_e32 v245, 0xffff0000, v187
	v_fmac_f32_e32 v222, v238, v46
	v_fmac_f32_e32 v230, v238, v46
	v_fmac_f32_e32 v223, v239, v46
	v_fmac_f32_e32 v231, v239, v46
	v_fmac_f32_e32 v224, v240, v46
	v_fmac_f32_e32 v232, v240, v46
	v_fmac_f32_e32 v225, v241, v46
	v_fmac_f32_e32 v233, v241, v46
	v_fmac_f32_e32 v226, v242, v46
	v_fmac_f32_e32 v234, v242, v46
	v_fmac_f32_e32 v227, v243, v46
	v_fmac_f32_e32 v235, v243, v46
	v_fmac_f32_e32 v228, v244, v46
	v_fmac_f32_e32 v236, v244, v46
	v_fmac_f32_e32 v229, v245, v46
	v_fmac_f32_e32 v237, v245, v46
	v_lshlrev_b32_e32 v238, 16, v188
	v_and_b32_e32 v239, 0xffff0000, v188
	v_lshlrev_b32_e32 v240, 16, v189
	v_and_b32_e32 v241, 0xffff0000, v189
	v_lshlrev_b32_e32 v242, 16, v190
	v_and_b32_e32 v243, 0xffff0000, v190
	v_lshlrev_b32_e32 v244, 16, v191
	v_and_b32_e32 v245, 0xffff0000, v191
	v_fmac_f32_e32 v222, v238, v47
	v_fmac_f32_e32 v230, v238, v47
	v_fmac_f32_e32 v223, v239, v47
	v_fmac_f32_e32 v231, v239, v47
	v_fmac_f32_e32 v224, v240, v47
	v_fmac_f32_e32 v232, v240, v47
	v_fmac_f32_e32 v225, v241, v47
	v_fmac_f32_e32 v233, v241, v47
	v_fmac_f32_e32 v226, v242, v47
	v_fmac_f32_e32 v234, v242, v47
	v_fmac_f32_e32 v227, v243, v47
	v_fmac_f32_e32 v235, v243, v47
	v_fmac_f32_e32 v228, v244, v47
	v_fmac_f32_e32 v236, v244, v47
	v_fmac_f32_e32 v229, v245, v47
	v_fmac_f32_e32 v237, v245, v47
	v_lshlrev_b32_e32 v238, 16, v192
	v_and_b32_e32 v239, 0xffff0000, v192
	v_lshlrev_b32_e32 v240, 16, v193
	v_and_b32_e32 v241, 0xffff0000, v193
	v_lshlrev_b32_e32 v242, 16, v194
	v_and_b32_e32 v243, 0xffff0000, v194
	v_lshlrev_b32_e32 v244, 16, v195
	v_and_b32_e32 v245, 0xffff0000, v195
	v_fmac_f32_e32 v222, v238, v48
	v_fmac_f32_e32 v230, v238, v48
	v_fmac_f32_e32 v223, v239, v48
	v_fmac_f32_e32 v231, v239, v48
	v_fmac_f32_e32 v224, v240, v48
	v_fmac_f32_e32 v232, v240, v48
	v_fmac_f32_e32 v225, v241, v48
	v_fmac_f32_e32 v233, v241, v48
	v_fmac_f32_e32 v226, v242, v48
	v_fmac_f32_e32 v234, v242, v48
	v_fmac_f32_e32 v227, v243, v48
	v_fmac_f32_e32 v235, v243, v48
	v_fmac_f32_e32 v228, v244, v48
	v_fmac_f32_e32 v236, v244, v48
	v_fmac_f32_e32 v229, v245, v48
	v_fmac_f32_e32 v237, v245, v48
	v_lshlrev_b32_e32 v238, 16, v196
	v_and_b32_e32 v239, 0xffff0000, v196
	v_lshlrev_b32_e32 v240, 16, v197
	v_and_b32_e32 v241, 0xffff0000, v197
	v_lshlrev_b32_e32 v242, 16, v198
	v_and_b32_e32 v243, 0xffff0000, v198
	v_lshlrev_b32_e32 v244, 16, v199
	v_and_b32_e32 v245, 0xffff0000, v199
	v_fmac_f32_e32 v230, v238, v49
	v_fmac_f32_e32 v231, v239, v49
	v_fmac_f32_e32 v232, v240, v49
	v_fmac_f32_e32 v233, v241, v49
	v_fmac_f32_e32 v234, v242, v49
	v_fmac_f32_e32 v235, v243, v49
	v_fmac_f32_e32 v236, v244, v49
	v_fmac_f32_e32 v237, v245, v49
	v_fma_f32 v222, v222, v53, -v206
	v_fma_f32 v230, v230, v57, -v214
	v_fma_f32 v223, v223, v53, -v207
	v_fma_f32 v231, v231, v57, -v215
	v_fma_f32 v224, v224, v53, -v208
	v_fma_f32 v232, v232, v57, -v216
	v_fma_f32 v225, v225, v53, -v209
	v_fma_f32 v233, v233, v57, -v217
	v_fma_f32 v226, v226, v53, -v210
	v_fma_f32 v234, v234, v57, -v218
	v_fma_f32 v227, v227, v53, -v211
	v_fma_f32 v235, v235, v57, -v219
	v_fma_f32 v228, v228, v53, -v212
	v_fma_f32 v236, v236, v57, -v220
	v_fma_f32 v229, v229, v53, -v213
	v_fma_f32 v237, v237, v57, -v221
	v_cvt_pk_bf16_f32 v246, v222, v223
	v_cvt_pk_bf16_f32 v247, v224, v225
	v_cvt_pk_bf16_f32 v248, v226, v227
	v_cvt_pk_bf16_f32 v249, v228, v229
	global_store_dwordx4 v7, v[246:249], s[84:85] offset:1536
	s_nop 1
	v_cvt_pk_bf16_f32 v250, v230, v231
	v_cvt_pk_bf16_f32 v251, v232, v233
	v_cvt_pk_bf16_f32 v252, v234, v235
	v_cvt_pk_bf16_f32 v253, v236, v237
	global_store_dwordx4 v7, v[250:253], s[84:85] offset:-512
	s_nop 1
	v_add_u32_e32 v2, 0x40000, v2
	s_cmp_gt_u32 s2, 7
	s_cbranch_scc1 .Lpoold_done
; __device__ __forceinline__ unsigned pk2(float lo, float hi) { const f32x2_t v = {lo, hi}; const bf16x2_t b = __builtin_convertvector(v, bf16x2_t); return __builtin_bit_cast(unsigned, b); }
; template <int W>
; __device__ __forceinline__ void pool_item(const Params& p, const bf16_t* PROJ, bf16_t* D, int r, int c0) {
;     ...
;     } else {
;         const int s = r - MP; cnt = (float)W; const float* sp = p.in[4] + (size_t)s * 15 * 1024 + c0;
;         f32x4 a[W - 1], b[W - 1];
; #pragma unroll
;         for (int i = 0; i < W - 1; ++i) { a[i] = *(const f32x4*)(sp + (size_t)(14 - i) * 1024); b[i] = *(const f32x4*)(sp + (size_t)(14 - i) * 1024 + 4); }
; #pragma unroll
;         for (int i = 0; i < W - 1; ++i) { sum[0] += a[i].x; sum[1] += a[i].y; sum[2] += a[i].z; sum[3] += a[i].w; sum[4] += b[i].x; sum[5] += b[i].y; sum[6] += b[i].z; sum[7] += b[i].w; }
;     }
;     const float inv = 1.0f / cnt; u32x4 o;
;     o.x = pk2(sum[0] * inv - uu[0], sum[1] * inv - uu[1]); o.y = pk2(sum[2] * inv - uu[2], sum[3] * inv - uu[3]);
;     o.z = pk2(sum[4] * inv - uu[4], sum[5] * inv - uu[5]); o.w = pk2(sum[6] * inv - uu[6], sum[7] * inv - uu[7]);
;     *(u32x4*)(D + (size_t)r * 1024 + c0) = o;
	v_lshrrev_b32_e32 v3, 5, v2
	v_and_b32_e32 v5, 31, v2
	v_lshlrev_b32_e32 v5, 4, v5
	v_mul_u32_u24_e32 v6, 0x4800, v3
	v_add_u32_e32 v6, v6, v5
	v_lshl_add_u32 v7, v3, 11, v5
	v_add_u32_e32 v8, 0xffffe000, v3
	v_mul_u32_u24_e32 v8, 0xf000, v8
	v_lshl_add_u32 v8, v5, 1, v8
	global_load_dwordx4 v[64:67], v6, s[28:29]
	s_add_u32 s88, s60, 0xe000
	s_addc_u32 s89, s61, 0
	global_load_dwordx4 v[68:71], v8, s[88:89]
	global_load_dwordx4 v[72:75], v8, s[88:89] offset:16
	s_waitcnt vmcnt(0)
	v_lshlrev_b32_e32 v220, 16, v64
	v_and_b32_e32 v221, 0xffff0000, v64
	v_lshlrev_b32_e32 v222, 16, v65
	v_and_b32_e32 v223, 0xffff0000, v65
	v_lshlrev_b32_e32 v224, 16, v66
	v_and_b32_e32 v225, 0xffff0000, v66
	v_lshlrev_b32_e32 v226, 16, v67
	v_and_b32_e32 v227, 0xffff0000, v67
	v_mov_b32_e32 v228, v220
	v_mov_b32_e32 v229, v221
	v_mov_b32_e32 v230, v222
	v_mov_b32_e32 v231, v223
	v_mov_b32_e32 v232, v224
	v_mov_b32_e32 v233, v225
	v_mov_b32_e32 v234, v226
	v_mov_b32_e32 v235, v227
	v_add_f32_e32 v228, v228, v68
	v_add_f32_e32 v229, v229, v69
	v_add_f32_e32 v230, v230, v70
	v_add_f32_e32 v231, v231, v71
	v_add_f32_e32 v232, v232, v72
	v_add_f32_e32 v233, v233, v73
	v_add_f32_e32 v234, v234, v74
	v_add_f32_e32 v235, v235, v75
	v_mov_b32_e32 v48, 0x3f000000
	v_fma_f32 v228, v228, v48, -v220
	v_fma_f32 v229, v229, v48, -v221
	v_fma_f32 v230, v230, v48, -v222
	v_fma_f32 v231, v231, v48, -v223
	v_fma_f32 v232, v232, v48, -v224
	v_fma_f32 v233, v233, v48, -v225
	v_fma_f32 v234, v234, v48, -v226
	v_fma_f32 v235, v235, v48, -v227
	v_cvt_pk_bf16_f32 v244, v228, v229
	v_cvt_pk_bf16_f32 v245, v230, v231
	v_cvt_pk_bf16_f32 v246, v232, v233
	v_cvt_pk_bf16_f32 v247, v234, v235
	global_store_dwordx4 v7, v[244:247], s[84:85]
	s_nop 1
	global_load_dwordx4 v[64:67], v6, s[28:29] offset:512
	s_add_u32 s88, s60, 0xe400
	s_addc_u32 s89, s61, 0
	global_load_dwordx4 v[68:71], v8, s[88:89]
	global_load_dwordx4 v[72:75], v8, s[88:89] offset:16
	s_add_u32 s88, s60, 0xd400
	s_addc_u32 s89, s61, 0
	global_load_dwordx4 v[76:79], v8, s[88:89]
	global_load_dwordx4 v[80:83], v8, s[88:89] offset:16
	s_add_u32 s88, s60, 0xc400
	s_addc_u32 s89, s61, 0
	global_load_dwordx4 v[84:87], v8, s[88:89]
	global_load_dwordx4 v[88:91], v8, s[88:89] offset:16
	s_waitcnt vmcnt(0)
	v_lshlrev_b32_e32 v220, 16, v64
	v_and_b32_e32 v221, 0xffff0000, v64
	v_lshlrev_b32_e32 v222, 16, v65
	v_and_b32_e32 v223, 0xffff0000, v65
	v_lshlrev_b32_e32 v224, 16, v66
	v_and_b32_e32 v225, 0xffff0000, v66
	v_lshlrev_b32_e32 v226, 16, v67
	v_and_b32_e32 v227, 0xffff0000, v67
	v_mov_b32_e32 v228, v220
	v_mov_b32_e32 v229, v221
	v_mov_b32_e32 v230, v222
	v_mov_b32_e32 v231, v223
	v_mov_b32_e32 v232, v224
	v_mov_b32_e32 v233, v225
	v_mov_b32_e32 v234, v226
	v_mov_b32_e32 v235, v227
	v_add_f32_e32 v228, v228, v68
	v_add_f32_e32 v229, v229, v69
	v_add_f32_e32 v230, v230, v70
	v_add_f32_e32 v231, v231, v71
	v_add_f32_e32 v232, v232, v72
	v_add_f32_e32 v233, v233, v73
	v_add_f32_e32 v234, v234, v74
	v_add_f32_e32 v235, v235, v75
	v_add_f32_e32 v228, v228, v76
	v_add_f32_e32 v229, v229, v77
	v_add_f32_e32 v230, v230, v78
	v_add_f32_e32 v231, v231, v79
	v_add_f32_e32 v232, v232, v80
	v_add_f32_e32 v233, v233, v81
	v_add_f32_e32 v234, v234, v82
	v_add_f32_e32 v235, v235, v83
	v_add_f32_e32 v228, v228, v84
	v_add_f32_e32 v229, v229, v85
	v_add_f32_e32 v230, v230, v86
	v_add_f32_e32 v231, v231, v87
	v_add_f32_e32 v232, v232, v88
	v_add_f32_e32 v233, v233, v89
	v_add_f32_e32 v234, v234, v90
	v_add_f32_e32 v235, v235, v91
	v_mov_b32_e32 v48, 0x3e800000
	v_fma_f32 v228, v228, v48, -v220
	v_fma_f32 v229, v229, v48, -v221
	v_fma_f32 v230, v230, v48, -v222
	v_fma_f32 v231, v231, v48, -v223
	v_fma_f32 v232, v232, v48, -v224
	v_fma_f32 v233, v233, v48, -v225
	v_fma_f32 v234, v234, v48, -v226
	v_fma_f32 v235, v235, v48, -v227
	v_cvt_pk_bf16_f32 v244, v228, v229
	v_cvt_pk_bf16_f32 v245, v230, v231
	v_cvt_pk_bf16_f32 v246, v232, v233
	v_cvt_pk_bf16_f32 v247, v234, v235
	global_store_dwordx4 v7, v[244:247], s[84:85] offset:512
	s_nop 1
	global_load_dwordx4 v[64:67], v6, s[28:29] offset:1024
	s_add_u32 s88, s60, 0xe800
	s_addc_u32 s89, s61, 0
	global_load_dwordx4 v[68:71], v8, s[88:89]
	global_load_dwordx4 v[72:75], v8, s[88:89] offset:16
	s_add_u32 s88, s60, 0xd800
	s_addc_u32 s89, s61, 0
	global_load_dwordx4 v[76:79], v8, s[88:89]
	global_load_dwordx4 v[80:83], v8, s[88:89] offset:16
	s_add_u32 s88, s60, 0xc800
	s_addc_u32 s89, s61, 0
	global_load_dwordx4 v[84:87], v8, s[88:89]
	global_load_dwordx4 v[88:91], v8, s[88:89] offset:16
	s_add_u32 s88, s60, 0xb800
	s_addc_u32 s89, s61, 0
	global_load_dwordx4 v[92:95], v8, s[88:89]
	global_load_dwordx4 v[96:99], v8, s[88:89] offset:16
	s_add_u32 s88, s60, 0xa800
	s_addc_u32 s89, s61, 0
	global_load_dwordx4 v[100:103], v8, s[88:89]
	global_load_dwordx4 v[104:107], v8, s[88:89] offset:16
	s_add_u32 s88, s60, 0x9800
	s_addc_u32 s89, s61, 0
	global_load_dwordx4 v[108:111], v8, s[88:89]
	global_load_dwordx4 v[112:115], v8, s[88:89] offset:16
	s_add_u32 s88, s60, 0x8800
	s_addc_u32 s89, s61, 0
	global_load_dwordx4 v[116:119], v8, s[88:89]
	global_load_dwordx4 v[120:123], v8, s[88:89] offset:16
	s_waitcnt vmcnt(0)
; __device__ __forceinline__ unsigned pk2(float lo, float hi) { const f32x2_t v = {lo, hi}; const bf16x2_t b = __builtin_convertvector(v, bf16x2_t); return __builtin_bit_cast(unsigned, b); }
; template <int W>
; __device__ __forceinline__ void pool_item(const Params& p, const bf16_t* PROJ, bf16_t* D, int r, int c0) {
;     ...
;     } else {
;         const int s = r - MP; cnt = (float)W; const float* sp = p.in[4] + (size_t)s * 15 * 1024 + c0;
;         f32x4 a[W - 1], b[W - 1];
; #pragma unroll
;         for (int i = 0; i < W - 1; ++i) { a[i] = *(const f32x4*)(sp + (size_t)(14 - i) * 1024); b[i] = *(const f32x4*)(sp + (size_t)(14 - i) * 1024 + 4); }
; #pragma unroll
;         for (int i = 0; i < W - 1; ++i) { sum[0] += a[i].x; sum[1] += a[i].y; sum[2] += a[i].z; sum[3] += a[i].w; sum[4] += b[i].x; sum[5] += b[i].y; sum[6] += b[i].z; sum[7] += b[i].w; }
;     }
;     const float inv = 1.0f / cnt; u32x4 o;
;     o.x = pk2(sum[0] * inv - uu[0], sum[1] * inv - uu[1]); o.y = pk2(sum[2] * inv - uu[2], sum[3] * inv - uu[3]);
;     o.z = pk2(sum[4] * inv - uu[4], sum[5] * inv - uu[5]); o.w = pk2(sum[6] * inv - uu[6], sum[7] * inv - uu[7]);
;     *(u32x4*)(D + (size_t)r * 1024 + c0) = o;
	v_lshlrev_b32_e32 v220, 16, v64
	v_and_b32_e32 v221, 0xffff0000, v64
	v_lshlrev_b32_e32 v222, 16, v65
	v_and_b32_e32 v223, 0xffff0000, v65
	v_lshlrev_b32_e32 v224, 16, v66
	v_and_b32_e32 v225, 0xffff0000, v66
	v_lshlrev_b32_e32 v226, 16, v67
	v_and_b32_e32 v227, 0xffff0000, v67
	v_mov_b32_e32 v228, v220
	v_mov_b32_e32 v229, v221
	v_mov_b32_e32 v230, v222
	v_mov_b32_e32 v231, v223
	v_mov_b32_e32 v232, v224
	v_mov_b32_e32 v233, v225
	v_mov_b32_e32 v234, v226
	v_mov_b32_e32 v235, v227
	v_add_f32_e32 v228, v228, v68
	v_add_f32_e32 v229, v229, v69
	v_add_f32_e32 v230, v230, v70
	v_add_f32_e32 v231, v231, v71
	v_add_f32_e32 v232, v232, v72
	v_add_f32_e32 v233, v233, v73
	v_add_f32_e32 v234, v234, v74
	v_add_f32_e32 v235, v235, v75
	v_add_f32_e32 v228, v228, v76
	v_add_f32_e32 v229, v229, v77
	v_add_f32_e32 v230, v230, v78
	v_add_f32_e32 v231, v231, v79
	v_add_f32_e32 v232, v232, v80
	v_add_f32_e32 v233, v233, v81
	v_add_f32_e32 v234, v234, v82
	v_add_f32_e32 v235, v235, v83
	v_add_f32_e32 v228, v228, v84
	v_add_f32_e32 v229, v229, v85
	v_add_f32_e32 v230, v230, v86
	v_add_f32_e32 v231, v231, v87
	v_add_f32_e32 v232, v232, v88
	v_add_f32_e32 v233, v233, v89
	v_add_f32_e32 v234, v234, v90
	v_add_f32_e32 v235, v235, v91
	v_add_f32_e32 v228, v228, v92
	v_add_f32_e32 v229, v229, v93
	v_add_f32_e32 v230, v230, v94
	v_add_f32_e32 v231, v231, v95
	v_add_f32_e32 v232, v232, v96
	v_add_f32_e32 v233, v233, v97
	v_add_f32_e32 v234, v234, v98
	v_add_f32_e32 v235, v235, v99
	v_add_f32_e32 v228, v228, v100
	v_add_f32_e32 v229, v229, v101
	v_add_f32_e32 v230, v230, v102
	v_add_f32_e32 v231, v231, v103
	v_add_f32_e32 v232, v232, v104
	v_add_f32_e32 v233, v233, v105
	v_add_f32_e32 v234, v234, v106
	v_add_f32_e32 v235, v235, v107
	v_add_f32_e32 v228, v228, v108
	v_add_f32_e32 v229, v229, v109
	v_add_f32_e32 v230, v230, v110
	v_add_f32_e32 v231, v231, v111
	v_add_f32_e32 v232, v232, v112
	v_add_f32_e32 v233, v233, v113
	v_add_f32_e32 v234, v234, v114
	v_add_f32_e32 v235, v235, v115
	v_add_f32_e32 v228, v228, v116
	v_add_f32_e32 v229, v229, v117
	v_add_f32_e32 v230, v230, v118
	v_add_f32_e32 v231, v231, v119
	v_add_f32_e32 v232, v232, v120
	v_add_f32_e32 v233, v233, v121
	v_add_f32_e32 v234, v234, v122
	v_add_f32_e32 v235, v235, v123
	v_mov_b32_e32 v48, 0x3e000000
	v_fma_f32 v228, v228, v48, -v220
	v_fma_f32 v229, v229, v48, -v221
	v_fma_f32 v230, v230, v48, -v222
	v_fma_f32 v231, v231, v48, -v223
	v_fma_f32 v232, v232, v48, -v224
	v_fma_f32 v233, v233, v48, -v225
	v_fma_f32 v234, v234, v48, -v226
	v_fma_f32 v235, v235, v48, -v227
	v_cvt_pk_bf16_f32 v244, v228, v229
	v_cvt_pk_bf16_f32 v245, v230, v231
	v_cvt_pk_bf16_f32 v246, v232, v233
	v_cvt_pk_bf16_f32 v247, v234, v235
	global_store_dwordx4 v7, v[244:247], s[84:85] offset:1024
	s_nop 1
	global_load_dwordx4 v[64:67], v6, s[28:29] offset:1536
	s_add_u32 s88, s60, 0xec00
	s_addc_u32 s89, s61, 0
	global_load_dwordx4 v[68:71], v8, s[88:89]
	global_load_dwordx4 v[72:75], v8, s[88:89] offset:16
	s_add_u32 s88, s60, 0xdc00
	s_addc_u32 s89, s61, 0
	global_load_dwordx4 v[76:79], v8, s[88:89]
	global_load_dwordx4 v[80:83], v8, s[88:89] offset:16
	s_add_u32 s88, s60, 0xcc00
	s_addc_u32 s89, s61, 0
	global_load_dwordx4 v[84:87], v8, s[88:89]
	global_load_dwordx4 v[88:91], v8, s[88:89] offset:16
	s_add_u32 s88, s60, 0xbc00
	s_addc_u32 s89, s61, 0
	global_load_dwordx4 v[92:95], v8, s[88:89]
	global_load_dwordx4 v[96:99], v8, s[88:89] offset:16
	s_add_u32 s88, s60, 0xac00
	s_addc_u32 s89, s61, 0
	global_load_dwordx4 v[100:103], v8, s[88:89]
	global_load_dwordx4 v[104:107], v8, s[88:89] offset:16
	s_add_u32 s88, s60, 0x9c00
	s_addc_u32 s89, s61, 0
	global_load_dwordx4 v[108:111], v8, s[88:89]
	global_load_dwordx4 v[112:115], v8, s[88:89] offset:16
	s_add_u32 s88, s60, 0x8c00
	s_addc_u32 s89, s61, 0
	global_load_dwordx4 v[116:119], v8, s[88:89]
	global_load_dwordx4 v[120:123], v8, s[88:89] offset:16
	s_add_u32 s88, s60, 0x7c00
	s_addc_u32 s89, s61, 0
	global_load_dwordx4 v[124:127], v8, s[88:89]
	global_load_dwordx4 v[128:131], v8, s[88:89] offset:16
	s_add_u32 s88, s60, 0x6c00
	s_addc_u32 s89, s61, 0
	global_load_dwordx4 v[132:135], v8, s[88:89]
	global_load_dwordx4 v[136:139], v8, s[88:89] offset:16
	s_add_u32 s88, s60, 0x5c00
	s_addc_u32 s89, s61, 0
	global_load_dwordx4 v[140:143], v8, s[88:89]
	global_load_dwordx4 v[144:147], v8, s[88:89] offset:16
	s_add_u32 s88, s60, 0x4c00
	s_addc_u32 s89, s61, 0
	global_load_dwordx4 v[148:151], v8, s[88:89]
	global_load_dwordx4 v[152:155], v8, s[88:89] offset:16
	s_add_u32 s88, s60, 0x3c00
	s_addc_u32 s89, s61, 0
	global_load_dwordx4 v[156:159], v8, s[88:89]
	global_load_dwordx4 v[160:163], v8, s[88:89] offset:16
	s_add_u32 s88, s60, 0x2c00
	s_addc_u32 s89, s61, 0
	global_load_dwordx4 v[164:167], v8, s[88:89]
	global_load_dwordx4 v[168:171], v8, s[88:89] offset:16
	s_add_u32 s88, s60, 0x1c00
	s_addc_u32 s89, s61, 0
	global_load_dwordx4 v[172:175], v8, s[88:89]
	global_load_dwordx4 v[176:179], v8, s[88:89] offset:16
	s_add_u32 s88, s60, 0xc00
	s_addc_u32 s89, s61, 0
	global_load_dwordx4 v[180:183], v8, s[88:89]
	global_load_dwordx4 v[184:187], v8, s[88:89] offset:16
	s_waitcnt vmcnt(0)
; __device__ __forceinline__ unsigned pk2(float lo, float hi) { const f32x2_t v = {lo, hi}; const bf16x2_t b = __builtin_convertvector(v, bf16x2_t); return __builtin_bit_cast(unsigned, b); }
; template <int W>
; __device__ __forceinline__ void pool_item(const Params& p, const bf16_t* PROJ, bf16_t* D, int r, int c0) {
;     ...
;     } else {
;         const int s = r - MP; cnt = (float)W; const float* sp = p.in[4] + (size_t)s * 15 * 1024 + c0;
;         f32x4 a[W - 1], b[W - 1];
; #pragma unroll
;         for (int i = 0; i < W - 1; ++i) { a[i] = *(const f32x4*)(sp + (size_t)(14 - i) * 1024); b[i] = *(const f32x4*)(sp + (size_t)(14 - i) * 1024 + 4); }
; #pragma unroll
;         for (int i = 0; i < W - 1; ++i) { sum[0] += a[i].x; sum[1] += a[i].y; sum[2] += a[i].z; sum[3] += a[i].w; sum[4] += b[i].x; sum[5] += b[i].y; sum[6] += b[i].z; sum[7] += b[i].w; }
;     }
;     const float inv = 1.0f / cnt; u32x4 o;
;     o.x = pk2(sum[0] * inv - uu[0], sum[1] * inv - uu[1]); o.y = pk2(sum[2] * inv - uu[2], sum[3] * inv - uu[3]);
;     o.z = pk2(sum[4] * inv - uu[4], sum[5] * inv - uu[5]); o.w = pk2(sum[6] * inv - uu[6], sum[7] * inv - uu[7]);
;     *(u32x4*)(D + (size_t)r * 1024 + c0) = o;
	v_lshlrev_b32_e32 v220, 16, v64
	v_and_b32_e32 v221, 0xffff0000, v64
	v_lshlrev_b32_e32 v222, 16, v65
	v_and_b32_e32 v223, 0xffff0000, v65
	v_lshlrev_b32_e32 v224, 16, v66
	v_and_b32_e32 v225, 0xffff0000, v66
	v_lshlrev_b32_e32 v226, 16, v67
	v_and_b32_e32 v227, 0xffff0000, v67
	v_mov_b32_e32 v228, v220
	v_mov_b32_e32 v229, v221
	v_mov_b32_e32 v230, v222
	v_mov_b32_e32 v231, v223
	v_mov_b32_e32 v232, v224
	v_mov_b32_e32 v233, v225
	v_mov_b32_e32 v234, v226
	v_mov_b32_e32 v235, v227
	v_add_f32_e32 v228, v228, v68
	v_add_f32_e32 v229, v229, v69
	v_add_f32_e32 v230, v230, v70
	v_add_f32_e32 v231, v231, v71
	v_add_f32_e32 v232, v232, v72
	v_add_f32_e32 v233, v233, v73
	v_add_f32_e32 v234, v234, v74
	v_add_f32_e32 v235, v235, v75
	v_add_f32_e32 v228, v228, v76
	v_add_f32_e32 v229, v229, v77
	v_add_f32_e32 v230, v230, v78
	v_add_f32_e32 v231, v231, v79
	v_add_f32_e32 v232, v232, v80
	v_add_f32_e32 v233, v233, v81
	v_add_f32_e32 v234, v234, v82
	v_add_f32_e32 v235, v235, v83
	v_add_f32_e32 v228, v228, v84
	v_add_f32_e32 v229, v229, v85
	v_add_f32_e32 v230, v230, v86
	v_add_f32_e32 v231, v231, v87
	v_add_f32_e32 v232, v232, v88
	v_add_f32_e32 v233, v233, v89
	v_add_f32_e32 v234, v234, v90
	v_add_f32_e32 v235, v235, v91
	v_add_f32_e32 v228, v228, v92
	v_add_f32_e32 v229, v229, v93
	v_add_f32_e32 v230, v230, v94
	v_add_f32_e32 v231, v231, v95
	v_add_f32_e32 v232, v232, v96
	v_add_f32_e32 v233, v233, v97
	v_add_f32_e32 v234, v234, v98
	v_add_f32_e32 v235, v235, v99
	v_add_f32_e32 v228, v228, v100
	v_add_f32_e32 v229, v229, v101
	v_add_f32_e32 v230, v230, v102
	v_add_f32_e32 v231, v231, v103
	v_add_f32_e32 v232, v232, v104
	v_add_f32_e32 v233, v233, v105
	v_add_f32_e32 v234, v234, v106
	v_add_f32_e32 v235, v235, v107
	v_add_f32_e32 v228, v228, v108
	v_add_f32_e32 v229, v229, v109
	v_add_f32_e32 v230, v230, v110
	v_add_f32_e32 v231, v231, v111
	v_add_f32_e32 v232, v232, v112
	v_add_f32_e32 v233, v233, v113
	v_add_f32_e32 v234, v234, v114
	v_add_f32_e32 v235, v235, v115
	v_add_f32_e32 v228, v228, v116
	v_add_f32_e32 v229, v229, v117
	v_add_f32_e32 v230, v230, v118
	v_add_f32_e32 v231, v231, v119
	v_add_f32_e32 v232, v232, v120
	v_add_f32_e32 v233, v233, v121
	v_add_f32_e32 v234, v234, v122
	v_add_f32_e32 v235, v235, v123
	v_add_f32_e32 v228, v228, v124
	v_add_f32_e32 v229, v229, v125
	v_add_f32_e32 v230, v230, v126
	v_add_f32_e32 v231, v231, v127
	v_add_f32_e32 v232, v232, v128
	v_add_f32_e32 v233, v233, v129
	v_add_f32_e32 v234, v234, v130
	v_add_f32_e32 v235, v235, v131
	v_add_f32_e32 v228, v228, v132
	v_add_f32_e32 v229, v229, v133
	v_add_f32_e32 v230, v230, v134
	v_add_f32_e32 v231, v231, v135
	v_add_f32_e32 v232, v232, v136
	v_add_f32_e32 v233, v233, v137
	v_add_f32_e32 v234, v234, v138
	v_add_f32_e32 v235, v235, v139
	v_add_f32_e32 v228, v228, v140
	v_add_f32_e32 v229, v229, v141
	v_add_f32_e32 v230, v230, v142
	v_add_f32_e32 v231, v231, v143
	v_add_f32_e32 v232, v232, v144
	v_add_f32_e32 v233, v233, v145
	v_add_f32_e32 v234, v234, v146
	v_add_f32_e32 v235, v235, v147
	v_add_f32_e32 v228, v228, v148
	v_add_f32_e32 v229, v229, v149
	v_add_f32_e32 v230, v230, v150
	v_add_f32_e32 v231, v231, v151
	v_add_f32_e32 v232, v232, v152
	v_add_f32_e32 v233, v233, v153
	v_add_f32_e32 v234, v234, v154
	v_add_f32_e32 v235, v235, v155
	v_add_f32_e32 v228, v228, v156
	v_add_f32_e32 v229, v229, v157
	v_add_f32_e32 v230, v230, v158
	v_add_f32_e32 v231, v231, v159
	v_add_f32_e32 v232, v232, v160
	v_add_f32_e32 v233, v233, v161
	v_add_f32_e32 v234, v234, v162
	v_add_f32_e32 v235, v235, v163
	v_add_f32_e32 v228, v228, v164
	v_add_f32_e32 v229, v229, v165
	v_add_f32_e32 v230, v230, v166
	v_add_f32_e32 v231, v231, v167
	v_add_f32_e32 v232, v232, v168
	v_add_f32_e32 v233, v233, v169
	v_add_f32_e32 v234, v234, v170
	v_add_f32_e32 v235, v235, v171
	v_add_f32_e32 v228, v228, v172
	v_add_f32_e32 v229, v229, v173
	v_add_f32_e32 v230, v230, v174
	v_add_f32_e32 v231, v231, v175
	v_add_f32_e32 v232, v232, v176
	v_add_f32_e32 v233, v233, v177
	v_add_f32_e32 v234, v234, v178
	v_add_f32_e32 v235, v235, v179
	v_add_f32_e32 v228, v228, v180
	v_add_f32_e32 v229, v229, v181
	v_add_f32_e32 v230, v230, v182
	v_add_f32_e32 v231, v231, v183
	v_add_f32_e32 v232, v232, v184
	v_add_f32_e32 v233, v233, v185
	v_add_f32_e32 v234, v234, v186
	v_add_f32_e32 v235, v235, v187
	v_mov_b32_e32 v48, 0x3d800000
	v_fma_f32 v228, v228, v48, -v220
	v_fma_f32 v229, v229, v48, -v221
	v_fma_f32 v230, v230, v48, -v222
	v_fma_f32 v231, v231, v48, -v223
	v_fma_f32 v232, v232, v48, -v224
	v_fma_f32 v233, v233, v48, -v225
	v_fma_f32 v234, v234, v48, -v226
	v_fma_f32 v235, v235, v48, -v227
	v_cvt_pk_bf16_f32 v244, v228, v229
	v_cvt_pk_bf16_f32 v245, v230, v231
	v_cvt_pk_bf16_f32 v246, v232, v233
	v_cvt_pk_bf16_f32 v247, v234, v235
	global_store_dwordx4 v7, v[244:247], s[84:85] offset:1536
	s_nop 1
